# attention softmax: mask-free copy of the score/exp region for tasks with all 256 key slots valid (t >= 255), uniform branch; -261 instructions on that path
# baseline (speedup 1.0000x reference)
; DI void attn_worker(unsigned char* ws, LAS unsigned char* lds, LAS unsigned* qctr, int wave) {
;     ...
;         float mx = -3.0e38f;
; #pragma unroll
;         for (int kt = 0; kt < 16; ++kt)
; #pragma unroll
;             for (int e = 0; e < 4; ++e) { const bool ok = (64 * kq + 4 * kt + e) < nvalid; s[kt][e] = ok ? s[kt][e] * 0.08838834764831845f : -3.0e38f; mx = fmaxf(mx, s[kt][e]); }
;         mx = fmaxf(mx, __shfl_xor(mx, 16)); mx = fmaxf(mx, __shfl_xor(mx, 32));
.LBB0_2282:
	s_or_b64 exec, exec, s[2:3]
	s_min_i32 s60, s33, 0xff
	s_cmpk_eq_i32 s60, 0xff
	s_cbranch_scc1 .Latt_fast
	v_mul_f32_e32 v80, 0x3db504f3, v24
	v_max_f32_e32 v80, 0xff61b1e6, v80
	v_cmp_lt_i32_e64 s[26:27], s60, v183
	v_mul_f32_e32 v81, 0x3db504f3, v25
	v_cmp_gt_i32_e64 s[34:35], s60, v183
	v_cndmask_b32_e64 v80, v80, v239, s[26:27]
	v_or_b32_e32 v82, 2, v183
	v_cndmask_b32_e64 v81, v239, v81, s[34:35]
	v_or_b32_e32 v83, 3, v183
	v_max_f32_e32 v80, v80, v81
	v_mul_f32_e32 v81, 0x3db504f3, v26
	v_cmp_lt_i32_e64 s[28:29], s60, v82
	v_mul_f32_e32 v82, 0x3db504f3, v27
	v_cmp_lt_i32_e64 s[30:31], s60, v83
	v_cndmask_b32_e64 v81, v81, v239, s[28:29]
	v_or_b32_e32 v83, 5, v183
	v_cndmask_b32_e64 v82, v82, v239, s[30:31]
	v_max3_f32 v80, v80, v81, v82
	v_or_b32_e32 v82, 4, v183
	v_mul_f32_e32 v81, 0x3db504f3, v40
	v_cmp_lt_i32_e64 s[22:23], s60, v82
	v_mul_f32_e32 v82, 0x3db504f3, v41
	v_cmp_lt_i32_e64 s[24:25], s60, v83
	v_cndmask_b32_e64 v81, v81, v239, s[22:23]
	v_or_b32_e32 v83, 7, v183
	v_cndmask_b32_e64 v82, v82, v239, s[24:25]
	v_max3_f32 v80, v80, v81, v82
	v_or_b32_e32 v82, 6, v183
	v_mul_f32_e32 v81, 0x3db504f3, v42
	v_cmp_lt_i32_e64 s[18:19], s60, v82
	v_mul_f32_e32 v82, 0x3db504f3, v43
	v_cmp_lt_i32_e64 s[20:21], s60, v83
	v_cndmask_b32_e64 v81, v81, v239, s[18:19]
	v_or_b32_e32 v83, 9, v183
	v_cndmask_b32_e64 v82, v82, v239, s[20:21]
	v_max3_f32 v80, v80, v81, v82
	v_or_b32_e32 v82, 8, v183
	v_mul_f32_e32 v81, 0x3db504f3, v44
	v_cmp_lt_i32_e64 s[14:15], s60, v82
	v_mul_f32_e32 v82, 0x3db504f3, v45
	v_cmp_lt_i32_e64 s[16:17], s60, v83
	v_cndmask_b32_e64 v81, v81, v239, s[14:15]
	v_or_b32_e32 v83, 11, v183
	v_cndmask_b32_e64 v82, v82, v239, s[16:17]
	v_max3_f32 v80, v80, v81, v82
	v_or_b32_e32 v82, 10, v183
	v_mul_f32_e32 v81, 0x3db504f3, v46
	v_cmp_lt_i32_e64 s[10:11], s60, v82
	v_mul_f32_e32 v82, 0x3db504f3, v47
	v_cmp_lt_i32_e64 s[12:13], s60, v83
	v_cndmask_b32_e64 v81, v81, v239, s[10:11]
	v_or_b32_e32 v83, 13, v183
	v_cndmask_b32_e64 v82, v82, v239, s[12:13]
	v_max3_f32 v80, v80, v81, v82
	v_or_b32_e32 v82, 12, v183
	v_mul_f32_e32 v81, 0x3db504f3, v76
	v_cmp_lt_i32_e64 s[6:7], s60, v82
	v_mul_f32_e32 v82, 0x3db504f3, v77
	v_cmp_lt_i32_e64 s[8:9], s60, v83
	v_cndmask_b32_e64 v81, v81, v239, s[6:7]
	v_or_b32_e32 v83, 15, v183
	v_cndmask_b32_e64 v82, v82, v239, s[8:9]
	v_max3_f32 v80, v80, v81, v82
	v_or_b32_e32 v82, 14, v183
	v_mul_f32_e32 v81, 0x3db504f3, v78
	v_cmp_lt_i32_e64 s[2:3], s60, v82
	v_mul_f32_e32 v82, 0x3db504f3, v79
	v_cmp_lt_i32_e64 s[4:5], s60, v83
	v_cndmask_b32_e64 v81, v81, v239, s[2:3]
	v_or_b32_e32 v83, 17, v183
	v_cndmask_b32_e64 v82, v82, v239, s[4:5]
	v_max3_f32 v80, v80, v81, v82
	v_or_b32_e32 v82, 16, v183
	v_mul_f32_e32 v81, 0x3db504f3, v28
	v_cmp_lt_i32_e32 vcc, s60, v82
	v_mul_f32_e32 v82, 0x3db504f3, v29
	v_cmp_lt_i32_e64 s[0:1], s60, v83
	v_cndmask_b32_e32 v81, v81, v239, vcc
	v_or_b32_e32 v83, 19, v183
	v_cndmask_b32_e64 v82, v82, v239, s[0:1]
	v_max3_f32 v80, v80, v81, v82
	v_or_b32_e32 v82, 18, v183
	v_mul_f32_e32 v81, 0x3db504f3, v30
	v_cmp_lt_i32_e64 s[36:37], s60, v82
	v_mul_f32_e32 v82, 0x3db504f3, v31
	v_cmp_lt_i32_e64 s[38:39], s60, v83
	v_cndmask_b32_e64 v81, v81, v239, s[36:37]
	v_cmp_lt_i32_e64 s[56:57], s60, v132
	v_cndmask_b32_e64 v82, v82, v239, s[38:39]
	v_max3_f32 v80, v80, v81, v82
	v_or_b32_e32 v82, 20, v183
	v_mul_f32_e32 v81, 0x3db504f3, v16
	v_cmp_lt_i32_e64 s[96:97], s60, v82
	v_mul_f32_e32 v82, 0x3db504f3, v17
	v_cndmask_b32_e64 v82, v82, v239, s[56:57]
	v_cndmask_b32_e64 v81, v81, v239, s[96:97]
	v_max3_f32 v80, v80, v81, v82
	v_mul_f32_e32 v81, 0x3db504f3, v18
	v_cmp_lt_i32_e64 s[52:53], s60, v185
	v_mul_f32_e32 v82, 0x3db504f3, v19
	v_cmp_lt_i32_e64 s[54:55], s60, v186
	v_cndmask_b32_e64 v81, v81, v239, s[52:53]
	v_cmp_lt_i32_e64 s[48:49], s60, v187
	v_cndmask_b32_e64 v82, v82, v239, s[54:55]
	v_max3_f32 v80, v80, v81, v82
	v_mul_f32_e32 v81, 0x3db504f3, v20
	v_mul_f32_e32 v82, 0x3db504f3, v21
	v_cmp_lt_i32_e64 s[50:51], s60, v188
	v_cndmask_b32_e64 v81, v81, v239, s[48:49]
	v_cmp_lt_i32_e64 s[44:45], s60, v189
	v_cndmask_b32_e64 v82, v82, v239, s[50:51]
	v_max3_f32 v80, v80, v81, v82
	v_mul_f32_e32 v81, 0x3db504f3, v22
	v_mul_f32_e32 v82, 0x3db504f3, v23
	v_cmp_lt_i32_e64 s[46:47], s60, v190
	v_cndmask_b32_e64 v81, v81, v239, s[44:45]
	v_cmp_lt_i32_e64 s[40:41], s60, v191
	v_cndmask_b32_e64 v82, v82, v239, s[46:47]
	v_max3_f32 v80, v80, v81, v82
	v_mul_f32_e32 v81, 0x3db504f3, v36
	v_writelane_b32 v253, s40, 9
	v_mul_f32_e32 v82, 0x3db504f3, v37
	v_cmp_lt_i32_e64 s[42:43], s60, v192
	v_writelane_b32 v253, s41, 10
	v_cndmask_b32_e64 v81, v81, v239, s[40:41]
	v_cndmask_b32_e64 v82, v82, v239, s[42:43]
	v_cmp_lt_i32_e64 s[40:41], s60, v193
	v_max3_f32 v80, v80, v81, v82
	v_mul_f32_e32 v81, 0x3db504f3, v38
	v_writelane_b32 v253, s40, 13
	v_mul_f32_e32 v82, 0x3db504f3, v39
	v_cmp_lt_i32_e64 s[94:95], s60, v208
	v_writelane_b32 v253, s41, 14
	v_cndmask_b32_e64 v81, v81, v239, s[40:41]
	v_cmp_lt_i32_e64 s[40:41], s60, v194
	v_cmp_lt_i32_e64 s[90:91], s60, v209
	v_cmp_lt_i32_e64 s[92:93], s60, v210
	v_writelane_b32 v253, s40, 11
	v_cmp_lt_i32_e64 s[86:87], s60, v211
	v_cmp_lt_i32_e64 s[88:89], s60, v212
	v_writelane_b32 v253, s41, 12
	v_cndmask_b32_e64 v82, v82, v239, s[40:41]
	v_cmp_lt_i32_e64 s[40:41], s60, v195
	v_max3_f32 v80, v80, v81, v82
	v_mul_f32_e32 v81, 0x3db504f3, v32
	v_writelane_b32 v253, s40, 17
	v_mul_f32_e32 v82, 0x3db504f3, v33
	v_cmp_lt_i32_e64 s[82:83], s60, v213
	v_writelane_b32 v253, s41, 18
	v_cndmask_b32_e64 v81, v81, v239, s[40:41]
	v_cmp_lt_i32_e64 s[40:41], s60, v196
	v_cmp_lt_i32_e64 s[84:85], s60, v214
	v_cmp_lt_i32_e64 s[80:81], s60, v216
; DI void attn_worker(unsigned char* ws, LAS unsigned char* lds, LAS unsigned* qctr, int wave) {
;     ...
;         float mx = -3.0e38f;
; #pragma unroll
;         for (int kt = 0; kt < 16; ++kt)
; #pragma unroll
;             for (int e = 0; e < 4; ++e) { const bool ok = (64 * kq + 4 * kt + e) < nvalid; s[kt][e] = ok ? s[kt][e] * 0.08838834764831845f : -3.0e38f; mx = fmaxf(mx, s[kt][e]); }
;         mx = fmaxf(mx, __shfl_xor(mx, 16)); mx = fmaxf(mx, __shfl_xor(mx, 32));
	v_writelane_b32 v253, s40, 15
	v_cmp_lt_i32_e64 s[74:75], s60, v217
	v_cmp_lt_i32_e64 s[76:77], s60, v218
	v_writelane_b32 v253, s41, 16
	v_cndmask_b32_e64 v82, v82, v239, s[40:41]
	v_cmp_lt_i32_e64 s[40:41], s60, v197
	v_max3_f32 v80, v80, v81, v82
	v_mul_f32_e32 v81, 0x3db504f3, v34
	v_writelane_b32 v253, s40, 21
	v_mul_f32_e32 v82, 0x3db504f3, v35
	v_cmp_lt_i32_e64 s[70:71], s60, v219
	v_writelane_b32 v253, s41, 22
	v_cndmask_b32_e64 v81, v81, v239, s[40:41]
	v_cmp_lt_i32_e64 s[40:41], s60, v198
	v_cmp_lt_i32_e64 s[72:73], s60, v220
	v_and_b32_e32 v84, 64, v235
	v_writelane_b32 v253, s40, 19
	v_cmp_lt_i32_e64 s[66:67], s60, v221
	v_cmp_lt_i32_e64 s[68:69], s60, v222
	v_writelane_b32 v253, s41, 20
	v_cndmask_b32_e64 v82, v82, v239, s[40:41]
	v_cmp_lt_i32_e64 s[40:41], s60, v199
	v_max3_f32 v80, v80, v81, v82
	v_mul_f32_e32 v81, 0x3db504f3, v60
	v_writelane_b32 v253, s40, 25
	v_mul_f32_e32 v82, 0x3db504f3, v61
	v_xor_b32_e32 v83, 16, v235
	v_writelane_b32 v253, s41, 26
	v_cndmask_b32_e64 v81, v81, v239, s[40:41]
	v_cmp_lt_i32_e64 s[40:41], s60, v200
	v_add_u32_e32 v84, 64, v84
	v_cmp_lt_i32_e64 s[58:59], v83, v84
	v_writelane_b32 v253, s40, 23
	v_xor_b32_e32 v85, 32, v235
	v_cmp_lt_i32_e64 s[62:63], s60, v223
	v_writelane_b32 v253, s41, 24
	v_cndmask_b32_e64 v82, v82, v239, s[40:41]
	v_cmp_lt_i32_e64 s[40:41], s60, v201
	v_max3_f32 v80, v80, v81, v82
	v_mul_f32_e32 v81, 0x3db504f3, v62
	v_writelane_b32 v253, s40, 29
	v_mul_f32_e32 v82, 0x3db504f3, v63
	v_cmp_lt_i32_e64 s[64:65], s60, v224
	v_writelane_b32 v253, s41, 30
	v_cndmask_b32_e64 v81, v81, v239, s[40:41]
	v_cmp_lt_i32_e64 s[40:41], s60, v202
	v_cndmask_b32_e64 v83, v235, v83, s[58:59]
	v_cmp_lt_i32_e64 s[58:59], v85, v84
	v_writelane_b32 v253, s40, 27
	v_lshlrev_b32_e32 v241, 2, v83
	v_cndmask_b32_e64 v84, v235, v85, s[58:59]
	v_writelane_b32 v253, s41, 28
	v_cndmask_b32_e64 v82, v82, v239, s[40:41]
	v_cmp_lt_i32_e64 s[40:41], s60, v203
	v_max3_f32 v80, v80, v81, v82
	v_mul_f32_e32 v81, 0x3db504f3, v52
	v_writelane_b32 v253, s40, 33
	v_mul_f32_e32 v82, 0x3db504f3, v53
	v_cmp_lt_i32_e64 s[58:59], s60, v225
	v_writelane_b32 v253, s41, 34
	v_cndmask_b32_e64 v81, v81, v239, s[40:41]
	v_cmp_lt_i32_e64 s[40:41], s60, v204
	v_lshlrev_b32_e32 v240, 2, v84
	s_nop 0
	v_writelane_b32 v253, s40, 31
	s_nop 1
	v_writelane_b32 v253, s41, 32
	v_cndmask_b32_e64 v82, v82, v239, s[40:41]
	v_cmp_lt_i32_e64 s[40:41], s60, v205
	v_max3_f32 v80, v80, v81, v82
	v_mul_f32_e32 v81, 0x3db504f3, v54
	v_writelane_b32 v253, s40, 37
	v_mul_f32_e32 v82, 0x3db504f3, v55
	s_nop 0
	v_writelane_b32 v253, s41, 38
	v_cndmask_b32_e64 v81, v81, v239, s[40:41]
	v_cmp_lt_i32_e64 s[40:41], s60, v206
	s_nop 1
	v_writelane_b32 v253, s40, 35
	s_nop 1
	v_cndmask_b32_e64 v82, v82, v239, s[40:41]
	v_writelane_b32 v253, s41, 36
	v_max3_f32 v80, v80, v81, v82
	v_mul_f32_e32 v81, 0x3db504f3, v48
	v_cmp_lt_i32_e64 s[40:41], s60, v207
	v_mul_f32_e32 v82, 0x3db504f3, v49
	v_cndmask_b32_e64 v82, v82, v239, s[94:95]
	v_writelane_b32 v253, s40, 39
	s_nop 1
	v_cndmask_b32_e64 v81, v81, v239, s[40:41]
	v_max3_f32 v80, v80, v81, v82
	v_mul_f32_e32 v81, 0x3db504f3, v50
	v_mul_f32_e32 v82, 0x3db504f3, v51
	v_cndmask_b32_e64 v81, v81, v239, s[90:91]
	v_cndmask_b32_e64 v82, v82, v239, s[92:93]
	v_max3_f32 v80, v80, v81, v82
	v_mul_f32_e32 v81, 0x3db504f3, v56
	v_mul_f32_e32 v82, 0x3db504f3, v57
	v_cndmask_b32_e64 v81, v81, v239, s[86:87]
	v_cndmask_b32_e64 v82, v82, v239, s[88:89]
	v_max3_f32 v80, v80, v81, v82
	v_mul_f32_e32 v81, 0x3db504f3, v58
	v_mul_f32_e32 v82, 0x3db504f3, v59
	v_cndmask_b32_e64 v81, v81, v239, s[82:83]
	v_cndmask_b32_e64 v82, v82, v239, s[84:85]
	v_writelane_b32 v253, s41, 40
	v_max3_f32 v80, v80, v81, v82
	v_mul_f32_e32 v81, 0x3db504f3, v64
	v_cmp_lt_i32_e64 s[40:41], s60, v215
	v_mul_f32_e32 v82, 0x3db504f3, v65
	v_cndmask_b32_e64 v82, v82, v239, s[80:81]
	v_cndmask_b32_e64 v81, v81, v239, s[40:41]
	v_max3_f32 v80, v80, v81, v82
	v_mul_f32_e32 v81, 0x3db504f3, v66
	v_mul_f32_e32 v82, 0x3db504f3, v67
	v_cndmask_b32_e64 v81, v81, v239, s[74:75]
	v_cndmask_b32_e64 v82, v82, v239, s[76:77]
	v_max3_f32 v80, v80, v81, v82
	v_mul_f32_e32 v81, 0x3db504f3, v72
	v_mul_f32_e32 v82, 0x3db504f3, v73
	v_cndmask_b32_e64 v81, v81, v239, s[70:71]
	v_cndmask_b32_e64 v82, v82, v239, s[72:73]
	v_max3_f32 v80, v80, v81, v82
	v_mul_f32_e32 v81, 0x3db504f3, v74
	v_mul_f32_e32 v82, 0x3db504f3, v75
	v_cndmask_b32_e64 v81, v81, v239, s[66:67]
	v_cndmask_b32_e64 v82, v82, v239, s[68:69]
	v_max3_f32 v80, v80, v81, v82
	v_mul_f32_e32 v81, 0x3db504f3, v68
	v_mul_f32_e32 v82, 0x3db504f3, v69
	v_cndmask_b32_e64 v81, v81, v239, s[62:63]
	v_cndmask_b32_e64 v82, v82, v239, s[64:65]
	v_max3_f32 v80, v80, v81, v82
	v_mul_f32_e32 v81, 0x3db504f3, v70
	v_mul_f32_e32 v82, 0x3db504f3, v71
	v_cmp_lt_i32_e64 s[60:61], s60, v226
	v_cndmask_b32_e64 v81, v81, v239, s[58:59]
	s_nop 0
	v_cndmask_b32_e64 v82, v82, v239, s[60:61]
	v_max3_f32 v80, v80, v81, v82
	ds_bpermute_b32 v81, v241, v80
	s_waitcnt lgkmcnt(0)
	v_max_f32_e32 v81, v81, v81
	v_max_f32_e32 v80, v80, v81
	ds_bpermute_b32 v81, v240, v80
	s_waitcnt lgkmcnt(0)
; #define LAS __attribute__((address_space(3)))
; #define ATT_FENCE() asm volatile("" ::: "memory")
; DI void attn_worker(unsigned char* ws, LAS unsigned char* lds, LAS unsigned* qctr, int wave) {
;     ...
;         v4i ix[3][2]; v4u vv[3][8];
; #pragma unroll
;         for (int ch = 0; ch < 2; ++ch) {
;             ix[ch][0] = *(const LAS v4i*)(idl + 64 * kg + 8 * ch); ix[ch][1] = *(const LAS v4i*)(idl + 64 * kg + 8 * ch + 4);
; #pragma unroll
;             for (int j = 0; j < 8; ++j) vv[ch][j] = *(const v4u*)(vbase + (size_t)ix[ch][j >> 2][j & 3] * KVD);
;             ATT_FENCE(); }
;     ...
;         float sum = 0.f;
; #pragma unroll
;         for (int kt = 0; kt < 16; ++kt)
; #pragma unroll
;             for (int e = 0; e < 4; ++e) { const bool ok = (64 * kq + 4 * kt + e) < nvalid; const float p = ok ? __expf(s[kt][e] - mx) : 0.f; s[kt][e] = p; sum += p; }
	v_max_f32_e32 v81, v81, v81
	v_max_f32_e32 v242, v80, v81
	v_fma_f32 v24, v24, s78, -v242
	v_mul_f32_e32 v24, 0x3fb8aa3b, v24
	v_exp_f32_e32 v24, v24
	v_fma_f32 v30, v30, s78, -v242
	v_mul_f32_e32 v30, 0x3fb8aa3b, v30
	v_fma_f32 v31, v31, s78, -v242
	v_cndmask_b32_e64 v124, v24, 0, s[26:27]
	v_fma_f32 v24, v25, s78, -v242
	v_mul_f32_e32 v24, 0x3fb8aa3b, v24
	v_exp_f32_e32 v24, v24
	v_exp_f32_e32 v30, v30
	v_mul_f32_e32 v31, 0x3fb8aa3b, v31
	v_fma_f32 v16, v16, s78, -v242
	v_cndmask_b32_e64 v125, 0, v24, s[34:35]
	v_fma_f32 v24, v26, s78, -v242
	v_mul_f32_e32 v24, 0x3fb8aa3b, v24
	v_exp_f32_e32 v24, v24
	v_exp_f32_e32 v31, v31
	v_mul_f32_e32 v16, 0x3fb8aa3b, v16
	v_fma_f32 v17, v17, s78, -v242
	v_cndmask_b32_e64 v128, v24, 0, s[28:29]
	v_fma_f32 v24, v27, s78, -v242
	v_mul_f32_e32 v24, 0x3fb8aa3b, v24
	v_exp_f32_e32 v24, v24
	v_exp_f32_e32 v16, v16
	v_mul_f32_e32 v17, 0x3fb8aa3b, v17
	v_fma_f32 v18, v18, s78, -v242
	v_cndmask_b32_e64 v129, v24, 0, s[30:31]
	v_fma_f32 v24, v40, s78, -v242
	v_mul_f32_e32 v24, 0x3fb8aa3b, v24
	v_exp_f32_e32 v24, v24
	v_exp_f32_e32 v17, v17
	v_mul_f32_e32 v18, 0x3fb8aa3b, v18
	v_fma_f32 v19, v19, s78, -v242
	v_cndmask_b32_e64 v130, v24, 0, s[22:23]
	v_fma_f32 v24, v41, s78, -v242
	v_mul_f32_e32 v24, 0x3fb8aa3b, v24
	v_exp_f32_e32 v24, v24
	v_cndmask_b32_e64 v30, v30, 0, s[36:37]
	v_exp_f32_e32 v18, v18
	v_mul_f32_e32 v19, 0x3fb8aa3b, v19
	v_cndmask_b32_e64 v131, v24, 0, s[24:25]
	v_fma_f32 v24, v42, s78, -v242
	v_mul_f32_e32 v24, 0x3fb8aa3b, v24
	v_exp_f32_e32 v24, v24
	v_cndmask_b32_e64 v31, v31, 0, s[38:39]
	v_exp_f32_e32 v19, v19
	v_cndmask_b32_e64 v16, v16, 0, s[96:97]
	v_cndmask_b32_e64 v148, v24, 0, s[18:19]
	v_fma_f32 v24, v43, s78, -v242
	v_mul_f32_e32 v24, 0x3fb8aa3b, v24
	v_exp_f32_e32 v24, v24
	v_cndmask_b32_e64 v17, v17, 0, s[56:57]
	v_fma_f32 v32, v32, s78, -v242
	v_mul_f32_e32 v32, 0x3fb8aa3b, v32
	v_cndmask_b32_e64 v149, v24, 0, s[20:21]
	v_fma_f32 v24, v44, s78, -v242
	v_mul_f32_e32 v24, 0x3fb8aa3b, v24
	v_exp_f32_e32 v24, v24
	v_exp_f32_e32 v32, v32
	v_fma_f32 v33, v33, s78, -v242
	v_mul_f32_e32 v33, 0x3fb8aa3b, v33
	v_cndmask_b32_e64 v126, v24, 0, s[14:15]
	v_fma_f32 v24, v45, s78, -v242
	v_mul_f32_e32 v24, 0x3fb8aa3b, v24
	v_exp_f32_e32 v24, v24
	v_exp_f32_e32 v33, v33
	v_fma_f32 v34, v34, s78, -v242
	v_mul_f32_e32 v34, 0x3fb8aa3b, v34
	v_cndmask_b32_e64 v127, v24, 0, s[16:17]
	v_fma_f32 v24, v46, s78, -v242
	v_mul_f32_e32 v24, 0x3fb8aa3b, v24
	v_exp_f32_e32 v24, v24
	v_exp_f32_e32 v34, v34
	v_fma_f32 v35, v35, s78, -v242
	v_mul_f32_e32 v35, 0x3fb8aa3b, v35
	v_cndmask_b32_e64 v144, v24, 0, s[10:11]
	v_fma_f32 v24, v47, s78, -v242
	v_mul_f32_e32 v24, 0x3fb8aa3b, v24
	v_exp_f32_e32 v24, v24
	v_exp_f32_e32 v35, v35
	v_cndmask_b32_e64 v145, v24, 0, s[12:13]
	v_fma_f32 v24, v76, s78, -v242
	v_mul_f32_e32 v24, 0x3fb8aa3b, v24
	v_exp_f32_e32 v24, v24
	s_nop 0
	v_cndmask_b32_e64 v146, v24, 0, s[6:7]
	v_fma_f32 v24, v77, s78, -v242
	v_mul_f32_e32 v24, 0x3fb8aa3b, v24
	v_exp_f32_e32 v24, v24
	s_nop 0
	v_cndmask_b32_e64 v147, v24, 0, s[8:9]
	v_fma_f32 v24, v78, s78, -v242
	v_mul_f32_e32 v24, 0x3fb8aa3b, v24
	v_exp_f32_e32 v24, v24
	s_nop 0
	v_cndmask_b32_e64 v150, v24, 0, s[2:3]
	v_fma_f32 v24, v79, s78, -v242
	v_mul_f32_e32 v24, 0x3fb8aa3b, v24
	v_exp_f32_e32 v24, v24
	s_nop 0
	v_cndmask_b32_e64 v151, v24, 0, s[4:5]
	v_fma_f32 v24, v28, s78, -v242
	v_mul_f32_e32 v24, 0x3fb8aa3b, v24
	v_exp_f32_e32 v24, v24
	s_nop 0
	v_cndmask_b32_e64 v28, v24, 0, vcc
	v_fma_f32 v24, v29, s78, -v242
	v_mul_f32_e32 v24, 0x3fb8aa3b, v24
	v_exp_f32_e32 v24, v24
	s_nop 0
	v_cndmask_b32_e64 v29, v24, 0, s[0:1]
	ds_read_b128 v[24:27], v182
	ds_read_b128 v[40:43], v182 offset:16
	v_readlane_b32 s0, v253, 9
	v_readlane_b32 s1, v253, 10
	s_waitcnt lgkmcnt(1)
	v_lshl_add_u32 v44, v24, 10, v252
	v_lshl_add_u32 v46, v25, 10, v252
	global_load_dwordx4 v[88:91], v44, s[100:101]
	global_load_dwordx4 v[92:95], v46, s[100:101]
	v_lshl_add_u32 v24, v26, 10, v252
	v_lshl_add_u32 v44, v27, 10, v252
	global_load_dwordx4 v[96:99], v24, s[100:101]
	global_load_dwordx4 v[100:103], v44, s[100:101]
	s_waitcnt lgkmcnt(0)
	v_lshl_add_u32 v24, v40, 10, v252
	v_lshl_add_u32 v26, v41, 10, v252
	global_load_dwordx4 v[104:107], v24, s[100:101]
	global_load_dwordx4 v[108:111], v26, s[100:101]
	v_lshl_add_u32 v24, v42, 10, v252
	v_lshl_add_u32 v26, v43, 10, v252
	global_load_dwordx4 v[112:115], v24, s[100:101]
	global_load_dwordx4 v[116:119], v26, s[100:101]
	ds_read_b128 v[42:45], v182 offset:32
	ds_read_b128 v[120:123], v182 offset:48
	s_waitcnt lgkmcnt(1)
	s_waitcnt lgkmcnt(0)
; DI void attn_worker(unsigned char* ws, LAS unsigned char* lds, LAS unsigned* qctr, int wave) {
;     ...
;         float sum = 0.f;
; #pragma unroll
;         for (int kt = 0; kt < 16; ++kt)
; #pragma unroll
;             for (int e = 0; e < 4; ++e) { const bool ok = (64 * kq + 4 * kt + e) < nvalid; const float p = ok ? __expf(s[kt][e] - mx) : 0.f; s[kt][e] = p; sum += p; }
;         sum += __shfl_xor(sum, 16); sum += __shfl_xor(sum, 32);
	v_lshl_add_u32 v80, v120, 10, v252
	v_add_f32_e32 v120, 0, v124
	v_add_f32_e32 v120, v125, v120
	v_add_f32_e32 v120, v128, v120
	v_add_f32_e32 v120, v129, v120
	v_add_f32_e32 v120, v130, v120
	v_add_f32_e32 v120, v131, v120
	v_add_f32_e32 v120, v148, v120
	v_add_f32_e32 v120, v149, v120
	v_add_f32_e32 v120, v126, v120
	v_add_f32_e32 v120, v127, v120
	v_add_f32_e32 v120, v144, v120
	v_add_f32_e32 v120, v145, v120
	v_add_f32_e32 v120, v146, v120
	v_add_f32_e32 v120, v147, v120
	v_add_f32_e32 v120, v150, v120
	v_add_f32_e32 v120, v151, v120
	v_add_f32_e32 v120, v28, v120
	v_add_f32_e32 v120, v29, v120
	v_add_f32_e32 v120, v30, v120
	v_add_f32_e32 v120, v31, v120
	v_add_f32_e32 v120, v16, v120
	v_lshl_add_u32 v82, v121, 10, v252
	v_add_f32_e32 v121, v17, v120
	v_cndmask_b32_e64 v120, v18, 0, s[52:53]
	v_add_f32_e32 v18, v120, v121
	v_cndmask_b32_e64 v121, v19, 0, s[54:55]
	v_fma_f32 v19, v20, s78, -v242
	v_fma_f32 v20, v21, s78, -v242
	v_mul_f32_e32 v19, 0x3fb8aa3b, v19
	v_mul_f32_e32 v20, 0x3fb8aa3b, v20
	v_exp_f32_e32 v19, v19
	v_exp_f32_e32 v20, v20
	v_add_f32_e32 v21, v121, v18
	v_lshl_add_u32 v24, v42, 10, v252
	v_cndmask_b32_e64 v18, v19, 0, s[48:49]
	v_cndmask_b32_e64 v19, v20, 0, s[50:51]
	v_fma_f32 v20, v22, s78, -v242
	v_mul_f32_e32 v20, 0x3fb8aa3b, v20
	v_fma_f32 v22, v23, s78, -v242
	v_exp_f32_e32 v20, v20
	v_mul_f32_e32 v22, 0x3fb8aa3b, v22
	v_exp_f32_e32 v22, v22
	v_add_f32_e32 v21, v18, v21
	v_add_f32_e32 v21, v19, v21
	v_cndmask_b32_e64 v20, v20, 0, s[44:45]
	v_add_f32_e32 v23, v20, v21
	v_cndmask_b32_e64 v21, v22, 0, s[46:47]
	v_fma_f32 v22, v36, s78, -v242
	v_mul_f32_e32 v22, 0x3fb8aa3b, v22
	v_fma_f32 v36, v37, s78, -v242
	v_exp_f32_e32 v22, v22
	v_mul_f32_e32 v36, 0x3fb8aa3b, v36
	v_exp_f32_e32 v36, v36
	v_add_f32_e32 v23, v21, v23
	v_cndmask_b32_e64 v22, v22, 0, s[0:1]
	v_add_f32_e32 v37, v22, v23
	v_cndmask_b32_e64 v23, v36, 0, s[42:43]
	v_fma_f32 v36, v38, s78, -v242
	v_mul_f32_e32 v36, 0x3fb8aa3b, v36
	v_exp_f32_e32 v36, v36
	v_fma_f32 v38, v39, s78, -v242
	v_mul_f32_e32 v38, 0x3fb8aa3b, v38
	v_exp_f32_e32 v38, v38
	v_readlane_b32 s0, v253, 13
	v_readlane_b32 s1, v253, 14
	v_add_f32_e32 v37, v23, v37
	s_nop 0
	v_cndmask_b32_e64 v36, v36, 0, s[0:1]
	v_readlane_b32 s0, v253, 11
	v_readlane_b32 s1, v253, 12
	v_add_f32_e32 v39, v36, v37
	v_lshl_add_u32 v26, v43, 10, v252
	v_cndmask_b32_e64 v37, v38, 0, s[0:1]
	v_readlane_b32 s0, v253, 17
	v_readlane_b32 s1, v253, 18
	v_add_f32_e32 v38, v37, v39
	v_fma_f32 v39, v60, s78, -v242
	v_cndmask_b32_e64 v32, v32, 0, s[0:1]
	v_readlane_b32 s0, v253, 15
	v_readlane_b32 s1, v253, 16
	v_mul_f32_e32 v39, 0x3fb8aa3b, v39
	v_exp_f32_e32 v39, v39
	v_cndmask_b32_e64 v33, v33, 0, s[0:1]
	v_readlane_b32 s0, v253, 21
	v_readlane_b32 s1, v253, 22
	v_fma_f32 v60, v61, s78, -v242
	v_mul_f32_e32 v60, 0x3fb8aa3b, v60
	v_cndmask_b32_e64 v34, v34, 0, s[0:1]
	v_readlane_b32 s0, v253, 19
	v_readlane_b32 s1, v253, 20
	v_exp_f32_e32 v60, v60
	v_add_f32_e32 v38, v32, v38
	v_cndmask_b32_e64 v35, v35, 0, s[0:1]
	v_readlane_b32 s0, v253, 25
	v_readlane_b32 s1, v253, 26
	v_add_f32_e32 v38, v33, v38
	v_add_f32_e32 v38, v34, v38
	v_cndmask_b32_e64 v152, v39, 0, s[0:1]
	v_fma_f32 v39, v62, s78, -v242
	v_mul_f32_e32 v39, 0x3fb8aa3b, v39
	v_readlane_b32 s0, v253, 23
	v_exp_f32_e32 v39, v39
	v_readlane_b32 s1, v253, 24
	v_add_f32_e32 v38, v35, v38
	v_add_f32_e32 v38, v152, v38
	v_cndmask_b32_e64 v153, v60, 0, s[0:1]
	v_fma_f32 v60, v63, s78, -v242
	v_readlane_b32 s0, v253, 29
	v_mul_f32_e32 v60, 0x3fb8aa3b, v60
	v_readlane_b32 s1, v253, 30
	v_exp_f32_e32 v60, v60
	v_add_f32_e32 v38, v153, v38
	v_cndmask_b32_e64 v156, v39, 0, s[0:1]
	v_fma_f32 v39, v52, s78, -v242
	v_mul_f32_e32 v39, 0x3fb8aa3b, v39
	v_readlane_b32 s0, v253, 27
	v_exp_f32_e32 v39, v39
	v_readlane_b32 s1, v253, 28
	v_fma_f32 v52, v53, s78, -v242
	v_mul_f32_e32 v52, 0x3fb8aa3b, v52
	v_cndmask_b32_e64 v157, v60, 0, s[0:1]
	v_readlane_b32 s0, v253, 33
	v_readlane_b32 s1, v253, 34
	v_exp_f32_e32 v52, v52
	v_add_f32_e32 v38, v156, v38
	v_cndmask_b32_e64 v154, v39, 0, s[0:1]
	v_fma_f32 v39, v54, s78, -v242
	v_mul_f32_e32 v39, 0x3fb8aa3b, v39
	v_readlane_b32 s0, v253, 31
	v_exp_f32_e32 v39, v39
	v_readlane_b32 s1, v253, 32
	v_add_f32_e32 v38, v157, v38
	v_add_f32_e32 v38, v154, v38
	v_cndmask_b32_e64 v155, v52, 0, s[0:1]
	v_fma_f32 v52, v55, s78, -v242
	v_readlane_b32 s0, v253, 37
	v_mul_f32_e32 v52, 0x3fb8aa3b, v52
	v_readlane_b32 s1, v253, 38
	v_exp_f32_e32 v52, v52
	v_add_f32_e32 v38, v155, v38
	v_cndmask_b32_e64 v158, v39, 0, s[0:1]
	v_fma_f32 v39, v48, s78, -v242
	v_mul_f32_e32 v39, 0x3fb8aa3b, v39
	v_fma_f32 v48, v49, s78, -v242
	v_readlane_b32 s0, v253, 35
	v_exp_f32_e32 v39, v39
	v_mul_f32_e32 v48, 0x3fb8aa3b, v48
	v_readlane_b32 s1, v253, 36
	v_exp_f32_e32 v48, v48
	v_add_f32_e32 v38, v158, v38
	v_cndmask_b32_e64 v159, v52, 0, s[0:1]
	v_readlane_b32 s0, v253, 39
	v_readlane_b32 s1, v253, 40
	v_cndmask_b32_e64 v161, v48, 0, s[94:95]
	v_fma_f32 v48, v51, s78, -v242
	v_cndmask_b32_e64 v160, v39, 0, s[0:1]
	v_fma_f32 v39, v50, s78, -v242
	v_mul_f32_e32 v39, 0x3fb8aa3b, v39
	v_exp_f32_e32 v39, v39
	v_mul_f32_e32 v48, 0x3fb8aa3b, v48
	v_exp_f32_e32 v48, v48
	v_add_f32_e32 v38, v159, v38
	v_cndmask_b32_e64 v164, v39, 0, s[90:91]
	v_fma_f32 v39, v56, s78, -v242
	v_cndmask_b32_e64 v165, v48, 0, s[92:93]
	v_mul_f32_e32 v39, 0x3fb8aa3b, v39
	v_fma_f32 v48, v57, s78, -v242
	v_exp_f32_e32 v39, v39
	v_mul_f32_e32 v48, 0x3fb8aa3b, v48
	v_exp_f32_e32 v48, v48
	v_add_f32_e32 v38, v160, v38
	v_cndmask_b32_e64 v162, v39, 0, s[86:87]
	v_fma_f32 v39, v58, s78, -v242
	v_cndmask_b32_e64 v163, v48, 0, s[88:89]
	v_mul_f32_e32 v39, 0x3fb8aa3b, v39
	v_fma_f32 v48, v59, s78, -v242
; DI v4u pack8(const f4& a, const f4& b) { v4u w; w.x = cvt_pk_bf16(a[0], a[1]); w.y = cvt_pk_bf16(a[2], a[3]); w.z = cvt_pk_bf16(b[0], b[1]); w.w = cvt_pk_bf16(b[2], b[3]); return w; }
; DI void attn_worker(unsigned char* ws, LAS unsigned char* lds, LAS unsigned* qctr, int wave) {
;     ...
;         float sum = 0.f;
; #pragma unroll
;         for (int kt = 0; kt < 16; ++kt)
; #pragma unroll
;             for (int e = 0; e < 4; ++e) { const bool ok = (64 * kq + 4 * kt + e) < nvalid; const float p = ok ? __expf(s[kt][e] - mx) : 0.f; s[kt][e] = p; sum += p; }
;         sum += __shfl_xor(sum, 16); sum += __shfl_xor(sum, 32);
;         const float inv = 1.0f / sum;
;         bf16x8 pa[8];
; #pragma unroll
;         for (int sg = 0; sg < 8; ++sg) pa[sg] = __builtin_bit_cast(bf16x8, epi::pack8(s[2 * sg] * inv, s[2 * sg + 1] * inv));
	v_exp_f32_e32 v39, v39
	v_mul_f32_e32 v48, 0x3fb8aa3b, v48
	v_exp_f32_e32 v48, v48
	v_add_f32_e32 v38, v161, v38
	v_cndmask_b32_e64 v166, v39, 0, s[82:83]
	v_fma_f32 v39, v64, s78, -v242
	v_cndmask_b32_e64 v167, v48, 0, s[84:85]
	v_mul_f32_e32 v39, 0x3fb8aa3b, v39
	v_fma_f32 v48, v65, s78, -v242
	v_exp_f32_e32 v39, v39
	v_mul_f32_e32 v48, 0x3fb8aa3b, v48
	v_exp_f32_e32 v48, v48
	v_add_f32_e32 v38, v164, v38
	v_cndmask_b32_e64 v168, v39, 0, s[40:41]
	v_fma_f32 v39, v66, s78, -v242
	v_cndmask_b32_e64 v169, v48, 0, s[80:81]
	v_mul_f32_e32 v39, 0x3fb8aa3b, v39
	v_fma_f32 v48, v67, s78, -v242
	v_exp_f32_e32 v39, v39
	v_mul_f32_e32 v48, 0x3fb8aa3b, v48
	v_exp_f32_e32 v48, v48
	v_add_f32_e32 v38, v165, v38
	v_cndmask_b32_e64 v170, v39, 0, s[74:75]
	v_fma_f32 v39, v72, s78, -v242
	v_cndmask_b32_e64 v171, v48, 0, s[76:77]
	v_mul_f32_e32 v39, 0x3fb8aa3b, v39
	v_fma_f32 v48, v73, s78, -v242
	v_exp_f32_e32 v39, v39
	v_mul_f32_e32 v48, 0x3fb8aa3b, v48
	v_exp_f32_e32 v48, v48
	v_add_f32_e32 v38, v162, v38
	v_cndmask_b32_e64 v72, v39, 0, s[70:71]
	v_fma_f32 v39, v74, s78, -v242
	v_cndmask_b32_e64 v73, v48, 0, s[72:73]
	v_mul_f32_e32 v39, 0x3fb8aa3b, v39
	v_fma_f32 v48, v75, s78, -v242
	v_exp_f32_e32 v39, v39
	v_mul_f32_e32 v48, 0x3fb8aa3b, v48
	v_exp_f32_e32 v48, v48
	v_add_f32_e32 v38, v163, v38
	v_cndmask_b32_e64 v74, v39, 0, s[66:67]
	v_fma_f32 v39, v68, s78, -v242
	v_add_f32_e32 v38, v166, v38
	v_cndmask_b32_e64 v75, v48, 0, s[68:69]
	v_mul_f32_e32 v39, 0x3fb8aa3b, v39
	v_fma_f32 v48, v69, s78, -v242
	v_add_f32_e32 v38, v167, v38
	v_exp_f32_e32 v39, v39
	v_mul_f32_e32 v48, 0x3fb8aa3b, v48
	v_add_f32_e32 v38, v168, v38
	v_exp_f32_e32 v48, v48
	v_add_f32_e32 v38, v169, v38
	v_add_f32_e32 v38, v170, v38
	v_add_f32_e32 v38, v171, v38
	v_cndmask_b32_e64 v68, v39, 0, s[62:63]
	v_fma_f32 v39, v70, s78, -v242
	v_add_f32_e32 v38, v72, v38
	v_cndmask_b32_e64 v69, v48, 0, s[64:65]
	v_mul_f32_e32 v39, 0x3fb8aa3b, v39
	v_fma_f32 v48, v71, s78, -v242
	v_add_f32_e32 v38, v73, v38
	v_exp_f32_e32 v39, v39
	v_mul_f32_e32 v48, 0x3fb8aa3b, v48
	v_add_f32_e32 v38, v74, v38
	v_exp_f32_e32 v48, v48
	v_add_f32_e32 v38, v75, v38
	v_add_f32_e32 v38, v68, v38
	v_add_f32_e32 v38, v69, v38
	v_cndmask_b32_e64 v70, v39, 0, s[58:59]
	v_add_f32_e32 v38, v70, v38
	v_cndmask_b32_e64 v71, v48, 0, s[60:61]
.Latt_join:
	v_add_f32_e32 v48, v71, v38
	ds_bpermute_b32 v49, v241, v48
	v_lshl_add_u32 v46, v44, 10, v252
	v_lshl_add_u32 v76, v45, 10, v252
	v_lshl_add_u32 v38, v122, 10, v252
	s_waitcnt lgkmcnt(0)
	v_add_f32_e32 v50, v48, v49
	v_lshl_add_u32 v48, v123, 10, v252
	v_mov_b32_e32 v40, v26
	v_mov_b32_e32 v84, v82
	global_load_dwordx4 v[24:27], v24, s[100:101]
	s_nop 0
	global_load_dwordx4 v[40:43], v40, s[100:101]
	s_nop 0
	global_load_dwordx4 v[44:47], v46, s[100:101]
	s_nop 0
	global_load_dwordx4 v[76:79], v76, s[100:101]
	s_nop 0
	global_load_dwordx4 v[80:83], v80, s[100:101]
	s_nop 0
	global_load_dwordx4 v[84:87], v84, s[100:101]
	global_load_dwordx4 v[52:55], v38, s[100:101]
	global_load_dwordx4 v[56:59], v48, s[100:101]
	ds_bpermute_b32 v51, v240, v50
	s_waitcnt lgkmcnt(0)
	v_add_f32_e32 v50, v50, v51
	v_div_scale_f32 v51, s[0:1], v50, v50, 1.0
	v_rcp_f32_e32 v60, v51
	s_nop 0
	v_fma_f32 v38, -v51, v60, 1.0
	v_fmac_f32_e32 v60, v38, v60
	v_div_scale_f32 v38, vcc, 1.0, v50, 1.0
	v_mul_f32_e32 v39, v38, v60
	v_fma_f32 v48, -v51, v39, v38
	v_fmac_f32_e32 v39, v48, v60
	v_fma_f32 v38, -v51, v39, v38
	v_div_fmas_f32 v38, v38, v60, v39
	v_div_fixup_f32 v122, v38, v50, 1.0
	v_pk_mul_f32 v[48:49], v[124:125], v[122:123] op_sel_hi:[1,0]
	v_pk_mul_f32 v[50:51], v[148:149], v[122:123] op_sel_hi:[1,0]
	v_pk_mul_f32 v[38:39], v[128:129], v[122:123] op_sel_hi:[1,0]
	v_pk_mul_f32 v[60:61], v[130:131], v[122:123] op_sel_hi:[1,0]
	v_cvt_pk_bf16_f32 v64, v48, v49
	v_cvt_pk_bf16_f32 v65, v38, v39
	v_pk_mul_f32 v[48:49], v[126:127], v[122:123] op_sel_hi:[1,0]
	v_cvt_pk_bf16_f32 v66, v60, v61
	v_cvt_pk_bf16_f32 v67, v50, v51
	v_pk_mul_f32 v[50:51], v[150:151], v[122:123] op_sel_hi:[1,0]
	v_pk_mul_f32 v[62:63], v[146:147], v[122:123] op_sel_hi:[1,0]
	v_pk_mul_f32 v[16:17], v[16:17], v[122:123] op_sel_hi:[1,0]
	v_pk_mul_f32 v[38:39], v[144:145], v[122:123] op_sel_hi:[1,0]
	v_cvt_pk_bf16_f32 v60, v48, v49
	v_pk_mul_f32 v[30:31], v[30:31], v[122:123] op_sel_hi:[1,0]
	v_cvt_pk_bf16_f32 v61, v38, v39
	v_cvt_pk_bf16_f32 v62, v62, v63
	v_cvt_pk_bf16_f32 v63, v50, v51
	v_pk_mul_f32 v[28:29], v[28:29], v[122:123] op_sel_hi:[1,0]
	v_pk_mul_f32 v[18:19], v[18:19], v[122:123] op_sel_hi:[1,0]
	v_cvt_pk_bf16_f32 v48, v28, v29
	v_cvt_pk_bf16_f32 v49, v30, v31
	v_cvt_pk_bf16_f32 v50, v16, v17
	v_pk_mul_f32 v[16:17], v[20:21], v[122:123] op_sel_hi:[1,0]
	v_pk_mul_f32 v[38:39], v[120:121], v[122:123] op_sel_hi:[1,0]
	v_pk_mul_f32 v[20:21], v[36:37], v[122:123] op_sel_hi:[1,0]
	v_cvt_pk_bf16_f32 v51, v38, v39
	v_pk_mul_f32 v[22:23], v[22:23], v[122:123] op_sel_hi:[1,0]
	v_cvt_pk_bf16_f32 v36, v18, v19
	v_cvt_pk_bf16_f32 v37, v16, v17
	v_pk_mul_f32 v[16:17], v[34:35], v[122:123] op_sel_hi:[1,0]
	v_pk_mul_f32 v[18:19], v[32:33], v[122:123] op_sel_hi:[1,0]
	v_cvt_pk_bf16_f32 v38, v22, v23
	v_cvt_pk_bf16_f32 v39, v20, v21
	v_pk_mul_f32 v[20:21], v[156:157], v[122:123] op_sel_hi:[1,0]
	v_pk_mul_f32 v[22:23], v[152:153], v[122:123] op_sel_hi:[1,0]
	v_cvt_pk_bf16_f32 v32, v18, v19
	v_cvt_pk_bf16_f32 v33, v16, v17
	v_pk_mul_f32 v[16:17], v[158:159], v[122:123] op_sel_hi:[1,0]
	v_pk_mul_f32 v[18:19], v[154:155], v[122:123] op_sel_hi:[1,0]
	v_cvt_pk_bf16_f32 v34, v22, v23
	v_cvt_pk_bf16_f32 v35, v20, v21
	v_pk_mul_f32 v[20:21], v[164:165], v[122:123] op_sel_hi:[1,0]
	v_pk_mul_f32 v[22:23], v[160:161], v[122:123] op_sel_hi:[1,0]
	v_cvt_pk_bf16_f32 v28, v18, v19
	v_cvt_pk_bf16_f32 v29, v16, v17
	v_pk_mul_f32 v[16:17], v[166:167], v[122:123] op_sel_hi:[1,0]
	v_pk_mul_f32 v[18:19], v[162:163], v[122:123] op_sel_hi:[1,0]
	v_cvt_pk_bf16_f32 v30, v22, v23
	v_cvt_pk_bf16_f32 v31, v20, v21
	v_pk_mul_f32 v[120:121], v[170:171], v[122:123] op_sel_hi:[1,0]
	v_pk_mul_f32 v[22:23], v[168:169], v[122:123] op_sel_hi:[1,0]
	v_cvt_pk_bf16_f32 v20, v18, v19
	v_cvt_pk_bf16_f32 v21, v16, v17
	v_pk_mul_f32 v[18:19], v[74:75], v[122:123] op_sel_hi:[1,0]
	v_pk_mul_f32 v[16:17], v[72:73], v[122:123] op_sel_hi:[1,0]
	v_cvt_pk_bf16_f32 v22, v22, v23
	v_cvt_pk_bf16_f32 v23, v120, v121
	v_pk_mul_f32 v[70:71], v[70:71], v[122:123] op_sel_hi:[1,0]
	v_pk_mul_f32 v[68:69], v[68:69], v[122:123] op_sel_hi:[1,0]
	v_cvt_pk_bf16_f32 v16, v16, v17
	v_cvt_pk_bf16_f32 v17, v18, v19
	s_nop 0
	v_cvt_pk_bf16_f32 v18, v68, v69
	v_cvt_pk_bf16_f32 v19, v70, v71
	ds_read_b128 v[120:123], v182 offset:64
	ds_read_b128 v[124:127], v182 offset:80
	s_waitcnt lgkmcnt(1)
; #define LAS __attribute__((address_space(3)))
; #define ATT_FENCE() asm volatile("" ::: "memory")
; #define ATT_PV(nt_, ra_, rb_) acc[nt_] = __builtin_amdgcn_mfma_f32_16x16x32_bf16(pa[ch], __builtin_bit_cast(bf16x8, (v4u){ra_.x, ra_.y, rb_.x, rb_.y}), acc[nt_], 0, 0, 0)
; DI void attn_worker(unsigned char* ws, LAS unsigned char* lds, LAS unsigned* qctr, int wave) {
;     ...
;         for (int ch = 0; ch < 8; ++ch) {
;             if (ch + 2 < 8) { const int c2 = (ch + 2) % 3;
;                 ix[c2][0] = *(const LAS v4i*)(idl + 64 * kg + 8 * (ch + 2)); ix[c2][1] = *(const LAS v4i*)(idl + 64 * kg + 8 * (ch + 2) + 4);
; #pragma unroll
;                 for (int j = 0; j < 8; ++j) vv[c2][j] = *(const v4u*)(vbase + (size_t)ix[c2][j >> 2][j & 3] * KVD);
;                 ATT_FENCE(); }
; #pragma unroll
;             for (int j = 0; j < 8; ++j) *(LAS v4u*)(size_t)(vwb[j >> 2] + 64 * j) = vv[ch % 3][j];
;             v2u r0, r1, r2, r3, r4, r5, r6, r7, r8, r9, r10, r11, r12, r13, r14, r15;
;             asm volatile("ds_read_b64_tr_b16 %0, %16\n\tds_read_b64_tr_b16 %1, %18\n\tds_read_b64_tr_b16 %2, %17\n\tds_read_b64_tr_b16 %3, %19\n\t"
;                          "ds_read_b64_tr_b16 %4, %16 offset:512\n\tds_read_b64_tr_b16 %5, %18 offset:512\n\tds_read_b64_tr_b16 %6, %17 offset:512\n\tds_read_b64_tr_b16 %7, %19 offset:512\n\t"
;                          "ds_read_b64_tr_b16 %8, %16 offset:1024\n\tds_read_b64_tr_b16 %9, %18 offset:1024\n\tds_read_b64_tr_b16 %10, %17 offset:1024\n\tds_read_b64_tr_b16 %11, %19 offset:1024\n\t"
;                          "ds_read_b64_tr_b16 %12, %16 offset:1536\n\tds_read_b64_tr_b16 %13, %18 offset:1536\n\tds_read_b64_tr_b16 %14, %17 offset:1536\n\tds_read_b64_tr_b16 %15, %19 offset:1536\n\ts_waitcnt lgkmcnt(0)"
;                          : "=&v"(r0), "=&v"(r1), "=&v"(r2), "=&v"(r3), "=&v"(r4), "=&v"(r5), "=&v"(r6), "=&v"(r7), "=&v"(r8), "=&v"(r9), "=&v"(r10), "=&v"(r11), "=&v"(r12), "=&v"(r13), "=&v"(r14), "=&v"(r15)
;                          : "v"(vtb[0][0]), "v"(vtb[0][1]), "v"(vtb[1][0]), "v"(vtb[1][1]) : "memory");
;     ...
;             ATT_PV(0, r0, r1); ATT_PV(1, r2, r3); ATT_PV(2, r4, r5); ATT_PV(3, r6, r7); ATT_PV(4, r8, r9); ATT_PV(5, r10, r11); ATT_PV(6, r12, r13); ATT_PV(7, r14, r15);
	v_lshl_add_u32 v68, v120, 10, v252
	v_lshl_add_u32 v70, v121, 10, v252
	v_lshl_add_u32 v120, v122, 10, v252
	v_lshl_add_u32 v128, v123, 10, v252
	s_waitcnt lgkmcnt(0)
	v_lshl_add_u32 v144, v124, 10, v252
	v_lshl_add_u32 v146, v125, 10, v252
	v_mov_b32_e32 v124, v146
	v_mov_b32_e32 v72, v70
	global_load_dwordx4 v[68:71], v68, s[100:101]
	s_nop 0
	global_load_dwordx4 v[72:75], v72, s[100:101]
	s_nop 0
	global_load_dwordx4 v[120:123], v120, s[100:101]
	s_nop 0
	global_load_dwordx4 v[128:131], v128, s[100:101]
	s_nop 0
	global_load_dwordx4 v[144:147], v144, s[100:101]
	s_nop 0
	global_load_dwordx4 v[148:151], v124, s[100:101]
	v_lshl_add_u32 v124, v126, 10, v252
	v_lshl_add_u32 v152, v127, 10, v252
	global_load_dwordx4 v[124:127], v124, s[100:101]
	s_nop 0
	global_load_dwordx4 v[152:155], v152, s[100:101]
	s_waitcnt vmcnt(23)
	ds_write_b128 v236, v[88:91]
	s_waitcnt vmcnt(22)
	ds_write_b128 v236, v[92:95] offset:64
	s_waitcnt vmcnt(21)
	ds_write_b128 v236, v[96:99] offset:128
	s_waitcnt vmcnt(20)
	ds_write_b128 v236, v[100:103] offset:192
	s_waitcnt vmcnt(19)
	ds_write_b128 v237, v[104:107] offset:256
	s_waitcnt vmcnt(18)
	ds_write_b128 v237, v[108:111] offset:320
	s_waitcnt vmcnt(17)
	ds_write_b128 v237, v[112:115] offset:384
	s_waitcnt vmcnt(16)
	ds_write_b128 v237, v[116:119] offset:448
	ds_read_b64_tr_b16 v[116:117], v176
	ds_read_b64_tr_b16 v[118:119], v178
	ds_read_b64_tr_b16 v[112:113], v177
	ds_read_b64_tr_b16 v[114:115], v179
	ds_read_b64_tr_b16 v[108:109], v176 offset:512
	ds_read_b64_tr_b16 v[110:111], v178 offset:512
	ds_read_b64_tr_b16 v[104:105], v177 offset:512
	ds_read_b64_tr_b16 v[106:107], v179 offset:512
	ds_read_b64_tr_b16 v[100:101], v176 offset:1024
	ds_read_b64_tr_b16 v[102:103], v178 offset:1024
	ds_read_b64_tr_b16 v[96:97], v177 offset:1024
	ds_read_b64_tr_b16 v[98:99], v179 offset:1024
	ds_read_b64_tr_b16 v[92:93], v176 offset:1536
	ds_read_b64_tr_b16 v[94:95], v178 offset:1536
	ds_read_b64_tr_b16 v[88:89], v177 offset:1536
	ds_read_b64_tr_b16 v[90:91], v179 offset:1536
	s_waitcnt lgkmcnt(0)
	ds_read_b128 v[156:159], v182 offset:96
	ds_read_b128 v[164:167], v182 offset:112
	v_mfma_f32_16x16x32_bf16 v[116:119], v[64:67], v[116:119], 0
	s_waitcnt lgkmcnt(1)
	v_mfma_f32_16x16x32_bf16 v[112:115], v[64:67], v[112:115], 0
	v_lshl_add_u32 v168, v159, 10, v252
	s_waitcnt lgkmcnt(0)
	v_lshl_add_u32 v240, v164, 10, v252
	v_mfma_f32_16x16x32_bf16 v[108:111], v[64:67], v[108:111], 0
	v_lshl_add_u32 v242, v165, 10, v252
	v_mfma_f32_16x16x32_bf16 v[104:107], v[64:67], v[104:107], 0
	v_mov_b32_e32 v164, v242
	v_mfma_f32_16x16x32_bf16 v[100:103], v[64:67], v[100:103], 0
	v_lshl_add_u32 v248, v167, 10, v252
	v_mfma_f32_16x16x32_bf16 v[96:99], v[64:67], v[96:99], 0
	v_mfma_f32_16x16x32_bf16 v[92:95], v[64:67], v[92:95], 0
	v_mfma_f32_16x16x32_bf16 v[160:163], v[64:67], v[88:91], 0
	v_lshl_add_u32 v64, v156, 10, v252
	v_lshl_add_u32 v66, v157, 10, v252
	v_lshl_add_u32 v156, v158, 10, v252
	v_mov_b32_e32 v88, v66
	global_load_dwordx4 v[64:67], v64, s[100:101]
	s_nop 0
	global_load_dwordx4 v[88:91], v88, s[100:101]
	s_nop 0
	global_load_dwordx4 v[156:159], v156, s[100:101]
	s_nop 0
	global_load_dwordx4 v[168:171], v168, s[100:101]
	s_nop 0
	global_load_dwordx4 v[240:243], v240, s[100:101]
	s_nop 0
	global_load_dwordx4 v[244:247], v164, s[100:101]
	v_lshl_add_u32 v164, v166, 10, v252
	global_load_dwordx4 v[164:167], v164, s[100:101]
	s_nop 0
	global_load_dwordx4 v[248:251], v248, s[100:101]
	s_waitcnt vmcnt(23)
	ds_write_b128 v236, v[24:27]
	s_waitcnt vmcnt(22)
	ds_write_b128 v236, v[40:43] offset:64
	s_waitcnt vmcnt(21)
	ds_write_b128 v236, v[44:47] offset:128
	s_waitcnt vmcnt(20)
	ds_write_b128 v236, v[76:79] offset:192
	s_waitcnt vmcnt(19)
	ds_write_b128 v237, v[80:83] offset:256
	s_waitcnt vmcnt(18)
	ds_write_b128 v237, v[84:87] offset:320
	s_waitcnt vmcnt(17)
	ds_write_b128 v237, v[52:55] offset:384
	s_waitcnt vmcnt(16)
	ds_write_b128 v237, v[56:59] offset:448
	ds_read_b64_tr_b16 v[84:85], v176
	ds_read_b64_tr_b16 v[86:87], v178
	ds_read_b64_tr_b16 v[80:81], v177
	ds_read_b64_tr_b16 v[82:83], v179
	ds_read_b64_tr_b16 v[76:77], v176 offset:512
	ds_read_b64_tr_b16 v[78:79], v178 offset:512
	ds_read_b64_tr_b16 v[56:57], v177 offset:512
	ds_read_b64_tr_b16 v[58:59], v179 offset:512
	ds_read_b64_tr_b16 v[52:53], v176 offset:1024
	ds_read_b64_tr_b16 v[54:55], v178 offset:1024
	ds_read_b64_tr_b16 v[44:45], v177 offset:1024
	ds_read_b64_tr_b16 v[46:47], v179 offset:1024
	ds_read_b64_tr_b16 v[40:41], v176 offset:1536
	ds_read_b64_tr_b16 v[42:43], v178 offset:1536
	ds_read_b64_tr_b16 v[24:25], v177 offset:1536
	ds_read_b64_tr_b16 v[26:27], v179 offset:1536
	s_waitcnt lgkmcnt(0)
	s_nop 0
	v_mfma_f32_16x16x32_bf16 v[52:55], v[60:63], v[52:55], v[100:103]
	v_mfma_f32_16x16x32_bf16 v[44:47], v[60:63], v[44:47], v[96:99]
	s_nop 1
	ds_read_b128 v[100:103], v182 offset:144
	ds_read_b128 v[96:99], v182 offset:128
	v_mfma_f32_16x16x32_bf16 v[84:87], v[60:63], v[84:87], v[116:119]
	v_mfma_f32_16x16x32_bf16 v[80:83], v[60:63], v[80:83], v[112:115]
	s_waitcnt lgkmcnt(1)
	s_nop 0
	v_lshl_add_u32 v116, v103, 10, v252
	v_mfma_f32_16x16x32_bf16 v[76:79], v[60:63], v[76:79], v[108:111]
	v_mfma_f32_16x16x32_bf16 v[56:59], v[60:63], v[56:59], v[104:107]
	s_nop 1
	v_lshl_add_u32 v108, v100, 10, v252
	v_mfma_f32_16x16x32_bf16 v[92:95], v[60:63], v[40:43], v[92:95]
	s_waitcnt lgkmcnt(0)
; #define LAS __attribute__((address_space(3)))
; #define ATT_FENCE() asm volatile("" ::: "memory")
; #define ATT_PV(nt_, ra_, rb_) acc[nt_] = __builtin_amdgcn_mfma_f32_16x16x32_bf16(pa[ch], __builtin_bit_cast(bf16x8, (v4u){ra_.x, ra_.y, rb_.x, rb_.y}), acc[nt_], 0, 0, 0)
; DI void attn_worker(unsigned char* ws, LAS unsigned char* lds, LAS unsigned* qctr, int wave) {
;     ...
;         for (int ch = 0; ch < 8; ++ch) {
;             if (ch + 2 < 8) { const int c2 = (ch + 2) % 3;
;                 ix[c2][0] = *(const LAS v4i*)(idl + 64 * kg + 8 * (ch + 2)); ix[c2][1] = *(const LAS v4i*)(idl + 64 * kg + 8 * (ch + 2) + 4);
; #pragma unroll
;                 for (int j = 0; j < 8; ++j) vv[c2][j] = *(const v4u*)(vbase + (size_t)ix[c2][j >> 2][j & 3] * KVD);
;                 ATT_FENCE(); }
; #pragma unroll
;             for (int j = 0; j < 8; ++j) *(LAS v4u*)(size_t)(vwb[j >> 2] + 64 * j) = vv[ch % 3][j];
;             v2u r0, r1, r2, r3, r4, r5, r6, r7, r8, r9, r10, r11, r12, r13, r14, r15;
;             asm volatile("ds_read_b64_tr_b16 %0, %16\n\tds_read_b64_tr_b16 %1, %18\n\tds_read_b64_tr_b16 %2, %17\n\tds_read_b64_tr_b16 %3, %19\n\t"
;                          "ds_read_b64_tr_b16 %4, %16 offset:512\n\tds_read_b64_tr_b16 %5, %18 offset:512\n\tds_read_b64_tr_b16 %6, %17 offset:512\n\tds_read_b64_tr_b16 %7, %19 offset:512\n\t"
;                          "ds_read_b64_tr_b16 %8, %16 offset:1024\n\tds_read_b64_tr_b16 %9, %18 offset:1024\n\tds_read_b64_tr_b16 %10, %17 offset:1024\n\tds_read_b64_tr_b16 %11, %19 offset:1024\n\t"
;                          "ds_read_b64_tr_b16 %12, %16 offset:1536\n\tds_read_b64_tr_b16 %13, %18 offset:1536\n\tds_read_b64_tr_b16 %14, %17 offset:1536\n\tds_read_b64_tr_b16 %15, %19 offset:1536\n\ts_waitcnt lgkmcnt(0)"
;                          : "=&v"(r0), "=&v"(r1), "=&v"(r2), "=&v"(r3), "=&v"(r4), "=&v"(r5), "=&v"(r6), "=&v"(r7), "=&v"(r8), "=&v"(r9), "=&v"(r10), "=&v"(r11), "=&v"(r12), "=&v"(r13), "=&v"(r14), "=&v"(r15)
;                          : "v"(vtb[0][0]), "v"(vtb[0][1]), "v"(vtb[1][0]), "v"(vtb[1][1]) : "memory");
;     ...
;             ATT_PV(0, r0, r1); ATT_PV(1, r2, r3); ATT_PV(2, r4, r5); ATT_PV(3, r6, r7); ATT_PV(4, r8, r9); ATT_PV(5, r10, r11); ATT_PV(6, r12, r13); ATT_PV(7, r14, r15);
	v_lshl_add_u32 v104, v99, 10, v252
	v_lshl_add_u32 v110, v101, 10, v252
	v_mfma_f32_16x16x32_bf16 v[60:63], v[60:63], v[24:27], v[160:163]
	v_lshl_add_u32 v24, v96, 10, v252
	v_lshl_add_u32 v26, v97, 10, v252
	v_lshl_add_u32 v96, v98, 10, v252
	v_mov_b32_e32 v100, v110
	v_mov_b32_e32 v40, v26
	global_load_dwordx4 v[24:27], v24, s[100:101]
	s_nop 0
	global_load_dwordx4 v[40:43], v40, s[100:101]
	s_nop 0
	global_load_dwordx4 v[96:99], v96, s[100:101]
	s_nop 0
	global_load_dwordx4 v[104:107], v104, s[100:101]
	s_nop 0
	global_load_dwordx4 v[108:111], v108, s[100:101]
	s_nop 0
	global_load_dwordx4 v[112:115], v100, s[100:101]
	v_lshl_add_u32 v100, v102, 10, v252
	global_load_dwordx4 v[100:103], v100, s[100:101]
	s_nop 0
	global_load_dwordx4 v[116:119], v116, s[100:101]
	s_waitcnt vmcnt(23)
	ds_write_b128 v236, v[68:71]
	s_waitcnt vmcnt(22)
	ds_write_b128 v236, v[72:75] offset:64
	s_waitcnt vmcnt(21)
	ds_write_b128 v236, v[120:123] offset:128
	s_waitcnt vmcnt(20)
	ds_write_b128 v236, v[128:131] offset:192
	s_waitcnt vmcnt(19)
	ds_write_b128 v237, v[144:147] offset:256
	s_waitcnt vmcnt(18)
	ds_write_b128 v237, v[148:151] offset:320
	s_waitcnt vmcnt(17)
	ds_write_b128 v237, v[124:127] offset:384
	s_waitcnt vmcnt(16)
	ds_write_b128 v237, v[152:155] offset:448
	ds_read_b64_tr_b16 v[152:153], v176
	ds_read_b64_tr_b16 v[154:155], v178
	ds_read_b64_tr_b16 v[148:149], v177
	ds_read_b64_tr_b16 v[150:151], v179
	ds_read_b64_tr_b16 v[144:145], v176 offset:512
	ds_read_b64_tr_b16 v[146:147], v178 offset:512
	ds_read_b64_tr_b16 v[128:129], v177 offset:512
	ds_read_b64_tr_b16 v[130:131], v179 offset:512
	ds_read_b64_tr_b16 v[124:125], v176 offset:1024
	ds_read_b64_tr_b16 v[126:127], v178 offset:1024
	ds_read_b64_tr_b16 v[120:121], v177 offset:1024
	ds_read_b64_tr_b16 v[122:123], v179 offset:1024
	ds_read_b64_tr_b16 v[72:73], v176 offset:1536
	ds_read_b64_tr_b16 v[74:75], v178 offset:1536
	ds_read_b64_tr_b16 v[68:69], v177 offset:1536
	ds_read_b64_tr_b16 v[70:71], v179 offset:1536
	s_waitcnt lgkmcnt(0)
	s_nop 0
	v_mfma_f32_16x16x32_bf16 v[72:75], v[48:51], v[72:75], v[92:95]
	s_nop 2
	ds_read_b128 v[92:95], v182 offset:160
	v_mfma_f32_16x16x32_bf16 v[60:63], v[48:51], v[68:71], v[60:63]
	ds_read_b128 v[68:71], v182 offset:176
	v_mfma_f32_16x16x32_bf16 v[56:59], v[48:51], v[128:131], v[56:59]
	s_waitcnt lgkmcnt(0)
	v_lshl_add_u32 v128, v68, 10, v252
	v_mfma_f32_16x16x32_bf16 v[52:55], v[48:51], v[124:127], v[52:55]
	v_lshl_add_u32 v124, v95, 10, v252
	v_mfma_f32_16x16x32_bf16 v[120:123], v[48:51], v[120:123], v[44:47]
	v_lshl_add_u32 v130, v69, 10, v252
	v_mov_b32_e32 v68, v130
	v_lshl_add_u32 v44, v92, 10, v252
	v_lshl_add_u32 v46, v93, 10, v252
	v_lshl_add_u32 v92, v94, 10, v252
	v_mfma_f32_16x16x32_bf16 v[84:87], v[48:51], v[152:155], v[84:87]
	v_mfma_f32_16x16x32_bf16 v[80:83], v[48:51], v[148:151], v[80:83]
	v_mfma_f32_16x16x32_bf16 v[76:79], v[48:51], v[144:147], v[76:79]
	v_mov_b32_e32 v48, v46
	global_load_dwordx4 v[44:47], v44, s[100:101]
	s_nop 0
	global_load_dwordx4 v[48:51], v48, s[100:101]
	s_nop 0
	global_load_dwordx4 v[92:95], v92, s[100:101]
	s_nop 0
	global_load_dwordx4 v[124:127], v124, s[100:101]
	s_nop 0
	global_load_dwordx4 v[128:131], v128, s[100:101]
	s_nop 0
	global_load_dwordx4 v[144:147], v68, s[100:101]
	v_lshl_add_u32 v68, v70, 10, v252
	v_lshl_add_u32 v148, v71, 10, v252
	global_load_dwordx4 v[68:71], v68, s[100:101]
	s_nop 0
	global_load_dwordx4 v[148:151], v148, s[100:101]
	s_waitcnt vmcnt(23)
	ds_write_b128 v236, v[64:67]
	s_waitcnt vmcnt(22)
	ds_write_b128 v236, v[88:91] offset:64
	s_waitcnt vmcnt(21)
	ds_write_b128 v236, v[156:159] offset:128
	s_waitcnt vmcnt(20)
	ds_write_b128 v236, v[168:171] offset:192
	s_waitcnt vmcnt(19)
	ds_write_b128 v237, v[240:243] offset:256
	s_waitcnt vmcnt(18)
	ds_write_b128 v237, v[244:247] offset:320
	s_waitcnt vmcnt(17)
	ds_write_b128 v237, v[164:167] offset:384
	s_waitcnt vmcnt(16)
	ds_write_b128 v237, v[248:251] offset:448
	ds_read_b64_tr_b16 v[240:241], v176
	ds_read_b64_tr_b16 v[242:243], v178
	ds_read_b64_tr_b16 v[168:169], v177
	ds_read_b64_tr_b16 v[170:171], v179
	ds_read_b64_tr_b16 v[164:165], v176 offset:512
	ds_read_b64_tr_b16 v[166:167], v178 offset:512
	ds_read_b64_tr_b16 v[160:161], v177 offset:512
	ds_read_b64_tr_b16 v[162:163], v179 offset:512
	ds_read_b64_tr_b16 v[156:157], v176 offset:1024
	ds_read_b64_tr_b16 v[158:159], v178 offset:1024
	ds_read_b64_tr_b16 v[152:153], v177 offset:1024
	ds_read_b64_tr_b16 v[154:155], v179 offset:1024
	ds_read_b64_tr_b16 v[88:89], v176 offset:1536
	ds_read_b64_tr_b16 v[90:91], v178 offset:1536
	ds_read_b64_tr_b16 v[64:65], v177 offset:1536
	ds_read_b64_tr_b16 v[66:67], v179 offset:1536
	s_waitcnt lgkmcnt(0)
	s_nop 0
	v_mfma_f32_16x16x32_bf16 v[72:75], v[36:39], v[88:91], v[72:75]
	ds_read_b128 v[88:91], v182 offset:192
	v_mfma_f32_16x16x32_bf16 v[84:87], v[36:39], v[240:243], v[84:87]
	v_mfma_f32_16x16x32_bf16 v[80:83], v[36:39], v[168:171], v[80:83]
	v_mfma_f32_16x16x32_bf16 v[76:79], v[36:39], v[164:167], v[76:79]
	v_mfma_f32_16x16x32_bf16 v[56:59], v[36:39], v[160:163], v[56:59]
	v_mfma_f32_16x16x32_bf16 v[52:55], v[36:39], v[156:159], v[52:55]
	v_mfma_f32_16x16x32_bf16 v[120:123], v[36:39], v[152:155], v[120:123]
	v_mfma_f32_16x16x32_bf16 v[36:39], v[36:39], v[64:67], v[60:63]
	s_nop 2
	ds_read_b128 v[60:63], v182 offset:208
	s_waitcnt lgkmcnt(1)
	v_lshl_add_u32 v64, v88, 10, v252
	v_lshl_add_u32 v66, v89, 10, v252
	v_mov_b32_e32 v88, v66
	global_load_dwordx4 v[64:67], v64, s[100:101]
	s_nop 0
	global_load_dwordx4 v[152:155], v88, s[100:101]
	v_lshl_add_u32 v88, v90, 10, v252
	v_lshl_add_u32 v156, v91, 10, v252
	s_waitcnt lgkmcnt(0)
; #define LAS __attribute__((address_space(3)))
; #define ATT_FENCE() asm volatile("" ::: "memory")
; #define ATT_PV(nt_, ra_, rb_) acc[nt_] = __builtin_amdgcn_mfma_f32_16x16x32_bf16(pa[ch], __builtin_bit_cast(bf16x8, (v4u){ra_.x, ra_.y, rb_.x, rb_.y}), acc[nt_], 0, 0, 0)
; DI void attn_worker(unsigned char* ws, LAS unsigned char* lds, LAS unsigned* qctr, int wave) {
;     ...
;         for (int ch = 0; ch < 8; ++ch) {
;             if (ch + 2 < 8) { const int c2 = (ch + 2) % 3;
;                 ix[c2][0] = *(const LAS v4i*)(idl + 64 * kg + 8 * (ch + 2)); ix[c2][1] = *(const LAS v4i*)(idl + 64 * kg + 8 * (ch + 2) + 4);
; #pragma unroll
;                 for (int j = 0; j < 8; ++j) vv[c2][j] = *(const v4u*)(vbase + (size_t)ix[c2][j >> 2][j & 3] * KVD);
;                 ATT_FENCE(); }
; #pragma unroll
;             for (int j = 0; j < 8; ++j) *(LAS v4u*)(size_t)(vwb[j >> 2] + 64 * j) = vv[ch % 3][j];
;             v2u r0, r1, r2, r3, r4, r5, r6, r7, r8, r9, r10, r11, r12, r13, r14, r15;
;             asm volatile("ds_read_b64_tr_b16 %0, %16\n\tds_read_b64_tr_b16 %1, %18\n\tds_read_b64_tr_b16 %2, %17\n\tds_read_b64_tr_b16 %3, %19\n\t"
;                          "ds_read_b64_tr_b16 %4, %16 offset:512\n\tds_read_b64_tr_b16 %5, %18 offset:512\n\tds_read_b64_tr_b16 %6, %17 offset:512\n\tds_read_b64_tr_b16 %7, %19 offset:512\n\t"
;                          "ds_read_b64_tr_b16 %8, %16 offset:1024\n\tds_read_b64_tr_b16 %9, %18 offset:1024\n\tds_read_b64_tr_b16 %10, %17 offset:1024\n\tds_read_b64_tr_b16 %11, %19 offset:1024\n\t"
;                          "ds_read_b64_tr_b16 %12, %16 offset:1536\n\tds_read_b64_tr_b16 %13, %18 offset:1536\n\tds_read_b64_tr_b16 %14, %17 offset:1536\n\tds_read_b64_tr_b16 %15, %19 offset:1536\n\ts_waitcnt lgkmcnt(0)"
;                          : "=&v"(r0), "=&v"(r1), "=&v"(r2), "=&v"(r3), "=&v"(r4), "=&v"(r5), "=&v"(r6), "=&v"(r7), "=&v"(r8), "=&v"(r9), "=&v"(r10), "=&v"(r11), "=&v"(r12), "=&v"(r13), "=&v"(r14), "=&v"(r15)
;                          : "v"(vtb[0][0]), "v"(vtb[0][1]), "v"(vtb[1][0]), "v"(vtb[1][1]) : "memory");
;     ...
;             ATT_PV(0, r0, r1); ATT_PV(1, r2, r3); ATT_PV(2, r4, r5); ATT_PV(3, r6, r7); ATT_PV(4, r8, r9); ATT_PV(5, r10, r11); ATT_PV(6, r12, r13); ATT_PV(7, r14, r15);
	v_lshl_add_u32 v160, v60, 10, v252
	v_lshl_add_u32 v162, v61, 10, v252
	v_mov_b32_e32 v60, v162
	global_load_dwordx4 v[88:91], v88, s[100:101]
	s_nop 0
	global_load_dwordx4 v[156:159], v156, s[100:101]
	s_nop 0
	global_load_dwordx4 v[160:163], v160, s[100:101]
	s_nop 0
	global_load_dwordx4 v[164:167], v60, s[100:101]
	v_lshl_add_u32 v60, v62, 10, v252
	v_lshl_add_u32 v168, v63, 10, v252
	global_load_dwordx4 v[60:63], v60, s[100:101]
	s_nop 0
	global_load_dwordx4 v[168:171], v168, s[100:101]
	s_waitcnt vmcnt(23)
	ds_write_b128 v236, v[24:27]
	s_waitcnt vmcnt(22)
	ds_write_b128 v236, v[40:43] offset:64
	s_waitcnt vmcnt(21)
	ds_write_b128 v236, v[96:99] offset:128
	s_waitcnt vmcnt(20)
	ds_write_b128 v236, v[104:107] offset:192
	s_waitcnt vmcnt(19)
	ds_write_b128 v237, v[108:111] offset:256
	s_waitcnt vmcnt(18)
	ds_write_b128 v237, v[112:115] offset:320
	s_waitcnt vmcnt(17)
	ds_write_b128 v237, v[100:103] offset:384
	s_waitcnt vmcnt(16)
	ds_write_b128 v237, v[116:119] offset:448
	ds_read_b64_tr_b16 v[116:117], v176
	ds_read_b64_tr_b16 v[118:119], v178
	ds_read_b64_tr_b16 v[112:113], v177
	ds_read_b64_tr_b16 v[114:115], v179
	ds_read_b64_tr_b16 v[108:109], v176 offset:512
	ds_read_b64_tr_b16 v[110:111], v178 offset:512
	ds_read_b64_tr_b16 v[104:105], v177 offset:512
	ds_read_b64_tr_b16 v[106:107], v179 offset:512
	ds_read_b64_tr_b16 v[100:101], v176 offset:1024
	ds_read_b64_tr_b16 v[102:103], v178 offset:1024
	ds_read_b64_tr_b16 v[96:97], v177 offset:1024
	ds_read_b64_tr_b16 v[98:99], v179 offset:1024
	ds_read_b64_tr_b16 v[40:41], v176 offset:1536
	ds_read_b64_tr_b16 v[42:43], v178 offset:1536
	ds_read_b64_tr_b16 v[24:25], v177 offset:1536
	ds_read_b64_tr_b16 v[26:27], v179 offset:1536
	s_waitcnt lgkmcnt(0)
	s_nop 0
	v_mfma_f32_16x16x32_bf16 v[40:43], v[32:35], v[40:43], v[72:75]
	s_nop 2
	ds_read_b128 v[72:75], v182 offset:224
	v_mfma_f32_16x16x32_bf16 v[84:87], v[32:35], v[116:119], v[84:87]
	v_mfma_f32_16x16x32_bf16 v[80:83], v[32:35], v[112:115], v[80:83]
	v_mfma_f32_16x16x32_bf16 v[76:79], v[32:35], v[108:111], v[76:79]
	v_mfma_f32_16x16x32_bf16 v[56:59], v[32:35], v[104:107], v[56:59]
	v_mfma_f32_16x16x32_bf16 v[52:55], v[32:35], v[100:103], v[52:55]
	v_mfma_f32_16x16x32_bf16 v[96:99], v[32:35], v[96:99], v[120:123]
	v_mfma_f32_16x16x32_bf16 v[24:27], v[32:35], v[24:27], v[36:39]
	ds_read_b128 v[32:35], v182 offset:240
	s_waitcnt lgkmcnt(1)
	v_lshl_add_u32 v104, v75, 10, v252
	v_lshl_add_u32 v36, v72, 10, v252
	v_lshl_add_u32 v38, v73, 10, v252
	v_mov_b32_e32 v72, v38
	global_load_dwordx4 v[36:39], v36, s[100:101]
	s_nop 0
	global_load_dwordx4 v[100:103], v72, s[100:101]
	v_lshl_add_u32 v72, v74, 10, v252
	s_waitcnt lgkmcnt(0)
	v_lshl_add_u32 v108, v32, 10, v252
	v_lshl_add_u32 v110, v33, 10, v252
	v_mov_b32_e32 v32, v110
	global_load_dwordx4 v[72:75], v72, s[100:101]
	s_nop 0
	global_load_dwordx4 v[104:107], v104, s[100:101]
	s_nop 0
	global_load_dwordx4 v[108:111], v108, s[100:101]
	s_nop 0
	global_load_dwordx4 v[112:115], v32, s[100:101]
	v_lshl_add_u32 v32, v34, 10, v252
	v_lshl_add_u32 v116, v35, 10, v252
	global_load_dwordx4 v[32:35], v32, s[100:101]
	s_nop 0
	global_load_dwordx4 v[116:119], v116, s[100:101]
	s_waitcnt vmcnt(23)
	ds_write_b128 v236, v[44:47]
	s_waitcnt vmcnt(22)
	ds_write_b128 v236, v[48:51] offset:64
	s_waitcnt vmcnt(21)
	ds_write_b128 v236, v[92:95] offset:128
	s_waitcnt vmcnt(20)
	ds_write_b128 v236, v[124:127] offset:192
	s_waitcnt vmcnt(19)
	ds_write_b128 v237, v[128:131] offset:256
	s_waitcnt vmcnt(18)
	ds_write_b128 v237, v[144:147] offset:320
	s_waitcnt vmcnt(17)
	ds_write_b128 v237, v[68:71] offset:384
	s_waitcnt vmcnt(16)
	ds_write_b128 v237, v[148:151] offset:448
	ds_read_b64_tr_b16 v[144:145], v176
	ds_read_b64_tr_b16 v[146:147], v178
	ds_read_b64_tr_b16 v[128:129], v177
	ds_read_b64_tr_b16 v[130:131], v179
	ds_read_b64_tr_b16 v[124:125], v176 offset:512
	ds_read_b64_tr_b16 v[126:127], v178 offset:512
	ds_read_b64_tr_b16 v[120:121], v177 offset:512
	ds_read_b64_tr_b16 v[122:123], v179 offset:512
	ds_read_b64_tr_b16 v[92:93], v176 offset:1024
	ds_read_b64_tr_b16 v[94:95], v178 offset:1024
	ds_read_b64_tr_b16 v[68:69], v177 offset:1024
	ds_read_b64_tr_b16 v[70:71], v179 offset:1024
	ds_read_b64_tr_b16 v[48:49], v176 offset:1536
	ds_read_b64_tr_b16 v[50:51], v178 offset:1536
	ds_read_b64_tr_b16 v[44:45], v177 offset:1536
	ds_read_b64_tr_b16 v[46:47], v179 offset:1536
	s_waitcnt lgkmcnt(0)
	s_waitcnt vmcnt(15)
	ds_write_b128 v236, v[64:67]
	s_waitcnt vmcnt(14)
	ds_write_b128 v236, v[152:155] offset:64
	s_waitcnt vmcnt(13)
	ds_write_b128 v236, v[88:91] offset:128
	s_waitcnt vmcnt(12)
	ds_write_b128 v236, v[156:159] offset:192
	s_waitcnt vmcnt(11)
	ds_write_b128 v237, v[160:163] offset:256
	s_waitcnt vmcnt(10)
	ds_write_b128 v237, v[164:167] offset:320
	s_waitcnt vmcnt(9)
	ds_write_b128 v237, v[60:63] offset:384
	s_waitcnt vmcnt(8)
	ds_write_b128 v237, v[168:171] offset:448
	v_mfma_f32_16x16x32_bf16 v[84:87], v[28:31], v[144:147], v[84:87]
	v_mfma_f32_16x16x32_bf16 v[80:83], v[28:31], v[128:131], v[80:83]
	v_mfma_f32_16x16x32_bf16 v[76:79], v[28:31], v[124:127], v[76:79]
	v_mfma_f32_16x16x32_bf16 v[56:59], v[28:31], v[120:123], v[56:59]
	v_mfma_f32_16x16x32_bf16 v[52:55], v[28:31], v[92:95], v[52:55]
	v_mfma_f32_16x16x32_bf16 v[68:71], v[28:31], v[68:71], v[96:99]
	v_mfma_f32_16x16x32_bf16 v[40:43], v[28:31], v[48:51], v[40:43]
	v_mfma_f32_16x16x32_bf16 v[24:27], v[28:31], v[44:47], v[24:27]
	ds_read_b64_tr_b16 v[96:97], v176
	ds_read_b64_tr_b16 v[98:99], v178
	ds_read_b64_tr_b16 v[92:93], v177
	ds_read_b64_tr_b16 v[94:95], v179
	ds_read_b64_tr_b16 v[88:89], v176 offset:512
	ds_read_b64_tr_b16 v[90:91], v178 offset:512
	ds_read_b64_tr_b16 v[64:65], v177 offset:512
	ds_read_b64_tr_b16 v[66:67], v179 offset:512
	ds_read_b64_tr_b16 v[60:61], v176 offset:1024
	ds_read_b64_tr_b16 v[62:63], v178 offset:1024
	ds_read_b64_tr_b16 v[48:49], v177 offset:1024
	ds_read_b64_tr_b16 v[50:51], v179 offset:1024
	ds_read_b64_tr_b16 v[44:45], v176 offset:1536
	ds_read_b64_tr_b16 v[46:47], v178 offset:1536
	ds_read_b64_tr_b16 v[28:29], v177 offset:1536
	ds_read_b64_tr_b16 v[30:31], v179 offset:1536
	s_waitcnt lgkmcnt(0)
; #define LAS __attribute__((address_space(3)))
; #define ATT_FENCE() asm volatile("" ::: "memory")
; DI void attn_worker(unsigned char* ws, LAS unsigned char* lds, LAS unsigned* qctr, int wave) {
;     ...
;         for (int ch = 0; ch < 8; ++ch) {
;             if (ch + 2 < 8) { const int c2 = (ch + 2) % 3;
;                 ix[c2][0] = *(const LAS v4i*)(idl + 64 * kg + 8 * (ch + 2)); ix[c2][1] = *(const LAS v4i*)(idl + 64 * kg + 8 * (ch + 2) + 4);
; #pragma unroll
;                 for (int j = 0; j < 8; ++j) vv[c2][j] = *(const v4u*)(vbase + (size_t)ix[c2][j >> 2][j & 3] * KVD);
;                 ATT_FENCE(); }
; #pragma unroll
;             for (int j = 0; j < 8; ++j) *(LAS v4u*)(size_t)(vwb[j >> 2] + 64 * j) = vv[ch % 3][j];
;             v2u r0, r1, r2, r3, r4, r5, r6, r7, r8, r9, r10, r11, r12, r13, r14, r15;
;             asm volatile("ds_read_b64_tr_b16 %0, %16\n\tds_read_b64_tr_b16 %1, %18\n\tds_read_b64_tr_b16 %2, %17\n\tds_read_b64_tr_b16 %3, %19\n\t"
;                          "ds_read_b64_tr_b16 %4, %16 offset:512\n\tds_read_b64_tr_b16 %5, %18 offset:512\n\tds_read_b64_tr_b16 %6, %17 offset:512\n\tds_read_b64_tr_b16 %7, %19 offset:512\n\t"
;                          "ds_read_b64_tr_b16 %8, %16 offset:1024\n\tds_read_b64_tr_b16 %9, %18 offset:1024\n\tds_read_b64_tr_b16 %10, %17 offset:1024\n\tds_read_b64_tr_b16 %11, %19 offset:1024\n\t"
;                          "ds_read_b64_tr_b16 %12, %16 offset:1536\n\tds_read_b64_tr_b16 %13, %18 offset:1536\n\tds_read_b64_tr_b16 %14, %17 offset:1536\n\tds_read_b64_tr_b16 %15, %19 offset:1536\n\ts_waitcnt lgkmcnt(0)"
;                          : "=&v"(r0), "=&v"(r1), "=&v"(r2), "=&v"(r3), "=&v"(r4), "=&v"(r5), "=&v"(r6), "=&v"(r7), "=&v"(r8), "=&v"(r9), "=&v"(r10), "=&v"(r11), "=&v"(r12), "=&v"(r13), "=&v"(r14), "=&v"(r15)
;                          : "v"(vtb[0][0]), "v"(vtb[0][1]), "v"(vtb[1][0]), "v"(vtb[1][1]) : "memory");
;     ...
;             ATT_PV(0, r0, r1); ATT_PV(1, r2, r3); ATT_PV(2, r4, r5); ATT_PV(3, r6, r7); ATT_PV(4, r8, r9); ATT_PV(5, r10, r11); ATT_PV(6, r12, r13); ATT_PV(7, r14, r15);
;     ...
;         }
;         { LAS unsigned short* ob = (LAS unsigned short*)(lds + 2048);
;           if (lane < 16) {
; #pragma unroll
;             for (int nt = 0; nt < 8; ++nt)
; #pragma unroll
;                 for (int e = 0; e < 4; ++e) ob[e * 128 + 16 * nt + lane] = f2bf(acc[nt][e]); }
	s_waitcnt vmcnt(7)
	ds_write_b128 v236, v[36:39]
	s_waitcnt vmcnt(6)
	ds_write_b128 v236, v[100:103] offset:64
	s_waitcnt vmcnt(5)
	ds_write_b128 v236, v[72:75] offset:128
	s_waitcnt vmcnt(4)
	ds_write_b128 v236, v[104:107] offset:192
	s_waitcnt vmcnt(3)
	ds_write_b128 v237, v[108:111] offset:256
	s_waitcnt vmcnt(2)
	ds_write_b128 v237, v[112:115] offset:320
	s_waitcnt vmcnt(1)
	ds_write_b128 v237, v[32:35] offset:384
	s_waitcnt vmcnt(0)
	ds_write_b128 v237, v[116:119] offset:448
	v_mfma_f32_16x16x32_bf16 v[84:87], v[20:23], v[96:99], v[84:87]
	v_mfma_f32_16x16x32_bf16 v[80:83], v[20:23], v[92:95], v[80:83]
	v_mfma_f32_16x16x32_bf16 v[76:79], v[20:23], v[88:91], v[76:79]
	v_mfma_f32_16x16x32_bf16 v[56:59], v[20:23], v[64:67], v[56:59]
	v_mfma_f32_16x16x32_bf16 v[52:55], v[20:23], v[60:63], v[52:55]
	v_mfma_f32_16x16x32_bf16 v[48:51], v[20:23], v[48:51], v[68:71]
	v_mfma_f32_16x16x32_bf16 v[60:63], v[20:23], v[44:47], v[40:43]
	v_mfma_f32_16x16x32_bf16 v[64:67], v[20:23], v[28:31], v[24:27]
	ds_read_b64_tr_b16 v[44:45], v176
	ds_read_b64_tr_b16 v[46:47], v178
	ds_read_b64_tr_b16 v[40:41], v177
	ds_read_b64_tr_b16 v[42:43], v179
	ds_read_b64_tr_b16 v[36:37], v176 offset:512
	ds_read_b64_tr_b16 v[38:39], v178 offset:512
	ds_read_b64_tr_b16 v[32:33], v177 offset:512
	ds_read_b64_tr_b16 v[34:35], v179 offset:512
	ds_read_b64_tr_b16 v[28:29], v176 offset:1024
	ds_read_b64_tr_b16 v[30:31], v178 offset:1024
	ds_read_b64_tr_b16 v[24:25], v177 offset:1024
	ds_read_b64_tr_b16 v[26:27], v179 offset:1024
	ds_read_b64_tr_b16 v[20:21], v176 offset:1536
	ds_read_b64_tr_b16 v[22:23], v178 offset:1536
	ds_read_b64_tr_b16 v[68:69], v177 offset:1536
	ds_read_b64_tr_b16 v[70:71], v179 offset:1536
	s_waitcnt lgkmcnt(0)
	s_nop 0
	v_mfma_f32_16x16x32_bf16 v[44:47], v[16:19], v[44:47], v[84:87]
	v_mfma_f32_16x16x32_bf16 v[40:43], v[16:19], v[40:43], v[80:83]
	v_mfma_f32_16x16x32_bf16 v[36:39], v[16:19], v[36:39], v[76:79]
	v_mfma_f32_16x16x32_bf16 v[32:35], v[16:19], v[32:35], v[56:59]
	v_mfma_f32_16x16x32_bf16 v[28:31], v[16:19], v[28:31], v[52:55]
	v_mfma_f32_16x16x32_bf16 v[24:27], v[16:19], v[24:27], v[48:51]
	v_mfma_f32_16x16x32_bf16 v[20:23], v[16:19], v[20:23], v[60:63]
	v_mfma_f32_16x16x32_bf16 v[16:19], v[16:19], v[68:71], v[64:67]
	s_mov_b64 s[0:1], exec
	v_readlane_b32 s2, v253, 5
	v_readlane_b32 s3, v253, 6
	s_and_b64 s[2:3], s[0:1], s[2:3]
	s_mov_b64 exec, s[2:3]
	s_cbranch_execz .LBB0_2273
	v_bfe_u32 v48, v44, 16, 1
	v_add3_u32 v44, v44, v48, s79
	ds_write_b16_d16_hi v238, v44 offset:2048
	v_bfe_u32 v44, v45, 16, 1
	v_add3_u32 v44, v45, v44, s79
	ds_write_b16_d16_hi v238, v44 offset:2304
	v_bfe_u32 v44, v46, 16, 1
	v_add3_u32 v44, v46, v44, s79
	ds_write_b16_d16_hi v238, v44 offset:2560
	v_bfe_u32 v44, v47, 16, 1
	v_add3_u32 v44, v47, v44, s79
	ds_write_b16_d16_hi v238, v44 offset:2816
	v_bfe_u32 v44, v40, 16, 1
	v_add3_u32 v40, v40, v44, s79
	ds_write_b16_d16_hi v238, v40 offset:2080
	v_bfe_u32 v40, v41, 16, 1
	v_add3_u32 v40, v41, v40, s79
	ds_write_b16_d16_hi v238, v40 offset:2336
	v_bfe_u32 v40, v42, 16, 1
	v_add3_u32 v40, v42, v40, s79
	ds_write_b16_d16_hi v238, v40 offset:2592
	v_bfe_u32 v40, v43, 16, 1
	v_add3_u32 v40, v43, v40, s79
	ds_write_b16_d16_hi v238, v40 offset:2848
	v_bfe_u32 v40, v36, 16, 1
	v_add3_u32 v36, v36, v40, s79
	ds_write_b16_d16_hi v238, v36 offset:2112
	v_bfe_u32 v36, v37, 16, 1
	v_add3_u32 v36, v37, v36, s79
	ds_write_b16_d16_hi v238, v36 offset:2368
	v_bfe_u32 v36, v38, 16, 1
	v_add3_u32 v36, v38, v36, s79
	ds_write_b16_d16_hi v238, v36 offset:2624
	v_bfe_u32 v36, v39, 16, 1
	v_add3_u32 v36, v39, v36, s79
	ds_write_b16_d16_hi v238, v36 offset:2880
	v_bfe_u32 v36, v32, 16, 1
	v_add3_u32 v32, v32, v36, s79
	ds_write_b16_d16_hi v238, v32 offset:2144
	v_bfe_u32 v32, v33, 16, 1
	v_add3_u32 v32, v33, v32, s79
	ds_write_b16_d16_hi v238, v32 offset:2400
	v_bfe_u32 v32, v34, 16, 1
	v_add3_u32 v32, v34, v32, s79
	ds_write_b16_d16_hi v238, v32 offset:2656
	v_bfe_u32 v32, v35, 16, 1
	v_add3_u32 v32, v35, v32, s79
	ds_write_b16_d16_hi v238, v32 offset:2912
	v_bfe_u32 v32, v28, 16, 1
	v_add3_u32 v28, v28, v32, s79
	ds_write_b16_d16_hi v238, v28 offset:2176
	v_bfe_u32 v28, v29, 16, 1
	v_add3_u32 v28, v29, v28, s79
	ds_write_b16_d16_hi v238, v28 offset:2432
	v_bfe_u32 v28, v30, 16, 1
	v_add3_u32 v28, v30, v28, s79
	ds_write_b16_d16_hi v238, v28 offset:2688
	v_bfe_u32 v28, v31, 16, 1
	v_add3_u32 v28, v31, v28, s79
	ds_write_b16_d16_hi v238, v28 offset:2944
	v_bfe_u32 v28, v24, 16, 1
	v_add3_u32 v24, v24, v28, s79
	ds_write_b16_d16_hi v238, v24 offset:2208
	v_bfe_u32 v24, v25, 16, 1
	v_add3_u32 v24, v25, v24, s79
	ds_write_b16_d16_hi v238, v24 offset:2464
	v_bfe_u32 v24, v26, 16, 1
	v_add3_u32 v24, v26, v24, s79
	ds_write_b16_d16_hi v238, v24 offset:2720
	v_bfe_u32 v24, v27, 16, 1
	v_add3_u32 v24, v27, v24, s79
	ds_write_b16_d16_hi v238, v24 offset:2976
	v_bfe_u32 v24, v20, 16, 1
	v_add3_u32 v20, v20, v24, s79
	ds_write_b16_d16_hi v238, v20 offset:2240
	v_bfe_u32 v20, v21, 16, 1
	v_add3_u32 v20, v21, v20, s79
	ds_write_b16_d16_hi v238, v20 offset:2496
	v_bfe_u32 v20, v22, 16, 1
	v_add3_u32 v20, v22, v20, s79
	ds_write_b16_d16_hi v238, v20 offset:2752
	v_bfe_u32 v20, v23, 16, 1
	v_add3_u32 v20, v23, v20, s79
	ds_write_b16_d16_hi v238, v20 offset:3008
	v_bfe_u32 v20, v16, 16, 1
	v_add3_u32 v16, v16, v20, s79
	ds_write_b16_d16_hi v238, v16 offset:2272
	v_bfe_u32 v16, v17, 16, 1
	v_add3_u32 v16, v17, v16, s79
	ds_write_b16_d16_hi v238, v16 offset:2528
	v_bfe_u32 v16, v18, 16, 1
	v_add3_u32 v16, v18, v16, s79
	ds_write_b16_d16_hi v238, v16 offset:2784
	v_bfe_u32 v16, v19, 16, 1
	v_add3_u32 v16, v19, v16, s79
	ds_write_b16_d16_hi v238, v16 offset:3040
	s_branch .LBB0_2273
; DI void attn_worker(unsigned char* ws, LAS unsigned char* lds, LAS unsigned* qctr, int wave) {
;     ...
;         float mx = -3.0e38f;
; #pragma unroll
;         for (int kt = 0; kt < 16; ++kt)
; #pragma unroll
;             for (int e = 0; e < 4; ++e) { const bool ok = (64 * kq + 4 * kt + e) < nvalid; s[kt][e] = ok ? s[kt][e] * 0.08838834764831845f : -3.0e38f; mx = fmaxf(mx, s[kt][e]); }
;         mx = fmaxf(mx, __shfl_xor(mx, 16)); mx = fmaxf(mx, __shfl_xor(mx, 32));
;         float sum = 0.f;
; #pragma unroll
;         for (int kt = 0; kt < 16; ++kt)
; #pragma unroll
;             for (int e = 0; e < 4; ++e) { const bool ok = (64 * kq + 4 * kt + e) < nvalid; const float p = ok ? __expf(s[kt][e] - mx) : 0.f; s[kt][e] = p; sum += p; }
.Latt_fast:
	v_mul_f32_e32 v80, 0x3db504f3, v24
	v_max_f32_e32 v80, 0xff61b1e6, v80
	v_mul_f32_e32 v81, 0x3db504f3, v25
	v_max_f32_e32 v80, v80, v81
	v_mul_f32_e32 v81, 0x3db504f3, v26
	v_mul_f32_e32 v82, 0x3db504f3, v27
	v_max3_f32 v80, v80, v81, v82
	v_mul_f32_e32 v81, 0x3db504f3, v40
	v_mul_f32_e32 v82, 0x3db504f3, v41
	v_max3_f32 v80, v80, v81, v82
	v_mul_f32_e32 v81, 0x3db504f3, v42
	v_mul_f32_e32 v82, 0x3db504f3, v43
	v_max3_f32 v80, v80, v81, v82
	v_mul_f32_e32 v81, 0x3db504f3, v44
	v_mul_f32_e32 v82, 0x3db504f3, v45
	v_max3_f32 v80, v80, v81, v82
	v_mul_f32_e32 v81, 0x3db504f3, v46
	v_mul_f32_e32 v82, 0x3db504f3, v47
	v_max3_f32 v80, v80, v81, v82
	v_mul_f32_e32 v81, 0x3db504f3, v76
	v_mul_f32_e32 v82, 0x3db504f3, v77
	v_max3_f32 v80, v80, v81, v82
	v_mul_f32_e32 v81, 0x3db504f3, v78
	v_mul_f32_e32 v82, 0x3db504f3, v79
	v_max3_f32 v80, v80, v81, v82
	v_mul_f32_e32 v81, 0x3db504f3, v28
	v_mul_f32_e32 v82, 0x3db504f3, v29
	v_max3_f32 v80, v80, v81, v82
	v_mul_f32_e32 v81, 0x3db504f3, v30
	v_mul_f32_e32 v82, 0x3db504f3, v31
	v_max3_f32 v80, v80, v81, v82
	v_mul_f32_e32 v81, 0x3db504f3, v16
	v_mul_f32_e32 v82, 0x3db504f3, v17
	v_max3_f32 v80, v80, v81, v82
	v_mul_f32_e32 v81, 0x3db504f3, v18
	v_mul_f32_e32 v82, 0x3db504f3, v19
	v_max3_f32 v80, v80, v81, v82
	v_mul_f32_e32 v81, 0x3db504f3, v20
	v_mul_f32_e32 v82, 0x3db504f3, v21
	v_max3_f32 v80, v80, v81, v82
	v_mul_f32_e32 v81, 0x3db504f3, v22
	v_mul_f32_e32 v82, 0x3db504f3, v23
	v_max3_f32 v80, v80, v81, v82
	v_mul_f32_e32 v81, 0x3db504f3, v36
	v_mul_f32_e32 v82, 0x3db504f3, v37
	v_max3_f32 v80, v80, v81, v82
	v_mul_f32_e32 v81, 0x3db504f3, v38
	v_mul_f32_e32 v82, 0x3db504f3, v39
	v_max3_f32 v80, v80, v81, v82
	v_mul_f32_e32 v81, 0x3db504f3, v32
	v_mul_f32_e32 v82, 0x3db504f3, v33
	v_max3_f32 v80, v80, v81, v82
	v_mul_f32_e32 v81, 0x3db504f3, v34
	v_mul_f32_e32 v82, 0x3db504f3, v35
	v_and_b32_e32 v84, 64, v235
	v_max3_f32 v80, v80, v81, v82
	v_mul_f32_e32 v81, 0x3db504f3, v60
	v_mul_f32_e32 v82, 0x3db504f3, v61
	v_xor_b32_e32 v83, 16, v235
	v_add_u32_e32 v84, 64, v84
	v_cmp_lt_i32_e64 s[58:59], v83, v84
	v_xor_b32_e32 v85, 32, v235
	v_max3_f32 v80, v80, v81, v82
	v_mul_f32_e32 v81, 0x3db504f3, v62
	v_mul_f32_e32 v82, 0x3db504f3, v63
	v_cndmask_b32_e64 v83, v235, v83, s[58:59]
	v_cmp_lt_i32_e64 s[58:59], v85, v84
	v_lshlrev_b32_e32 v241, 2, v83
	s_nop 0
	v_cndmask_b32_e64 v84, v235, v85, s[58:59]
	v_max3_f32 v80, v80, v81, v82
	v_mul_f32_e32 v81, 0x3db504f3, v52
	v_mul_f32_e32 v82, 0x3db504f3, v53
	v_lshlrev_b32_e32 v240, 2, v84
	s_nop 0
	s_nop 1
	v_max3_f32 v80, v80, v81, v82
	v_mul_f32_e32 v81, 0x3db504f3, v54
	v_mul_f32_e32 v82, 0x3db504f3, v55
	s_nop 0
	s_nop 1
	s_nop 1
	v_max3_f32 v80, v80, v81, v82
	v_mul_f32_e32 v81, 0x3db504f3, v48
	v_mul_f32_e32 v82, 0x3db504f3, v49
	s_nop 1
	v_max3_f32 v80, v80, v81, v82
	v_mul_f32_e32 v81, 0x3db504f3, v50
	v_mul_f32_e32 v82, 0x3db504f3, v51
	v_max3_f32 v80, v80, v81, v82
	v_mul_f32_e32 v81, 0x3db504f3, v56
	v_mul_f32_e32 v82, 0x3db504f3, v57
	v_max3_f32 v80, v80, v81, v82
	v_mul_f32_e32 v81, 0x3db504f3, v58
	v_mul_f32_e32 v82, 0x3db504f3, v59
	v_max3_f32 v80, v80, v81, v82
	v_mul_f32_e32 v81, 0x3db504f3, v64
	v_mul_f32_e32 v82, 0x3db504f3, v65
	v_max3_f32 v80, v80, v81, v82
	v_mul_f32_e32 v81, 0x3db504f3, v66
	v_mul_f32_e32 v82, 0x3db504f3, v67
	v_max3_f32 v80, v80, v81, v82
	v_mul_f32_e32 v81, 0x3db504f3, v72
	v_mul_f32_e32 v82, 0x3db504f3, v73
	v_max3_f32 v80, v80, v81, v82
	v_mul_f32_e32 v81, 0x3db504f3, v74
	v_mul_f32_e32 v82, 0x3db504f3, v75
	v_max3_f32 v80, v80, v81, v82
	v_mul_f32_e32 v81, 0x3db504f3, v68
	v_mul_f32_e32 v82, 0x3db504f3, v69
	v_max3_f32 v80, v80, v81, v82
	v_mul_f32_e32 v81, 0x3db504f3, v70
	v_mul_f32_e32 v82, 0x3db504f3, v71
	s_nop 0
	v_max3_f32 v80, v80, v81, v82
	ds_bpermute_b32 v81, v241, v80
	s_waitcnt lgkmcnt(0)
	v_max_f32_e32 v81, v81, v81
	v_max_f32_e32 v80, v80, v81
	ds_bpermute_b32 v81, v240, v80
	s_waitcnt lgkmcnt(0)
	v_max_f32_e32 v81, v81, v81
	v_max_f32_e32 v242, v80, v81
	v_fma_f32 v24, v24, s78, -v242
	v_mul_f32_e32 v24, 0x3fb8aa3b, v24
	v_exp_f32_e32 v124, v24
	v_fma_f32 v30, v30, s78, -v242
	v_mul_f32_e32 v30, 0x3fb8aa3b, v30
	v_fma_f32 v31, v31, s78, -v242
	v_fma_f32 v24, v25, s78, -v242
	v_mul_f32_e32 v24, 0x3fb8aa3b, v24
	v_exp_f32_e32 v125, v24
	v_exp_f32_e32 v30, v30
	v_mul_f32_e32 v31, 0x3fb8aa3b, v31
	v_fma_f32 v16, v16, s78, -v242
	v_fma_f32 v24, v26, s78, -v242
	v_mul_f32_e32 v24, 0x3fb8aa3b, v24
	v_exp_f32_e32 v128, v24
	v_exp_f32_e32 v31, v31
	v_mul_f32_e32 v16, 0x3fb8aa3b, v16
	v_fma_f32 v17, v17, s78, -v242
	v_fma_f32 v24, v27, s78, -v242
	v_mul_f32_e32 v24, 0x3fb8aa3b, v24
	v_exp_f32_e32 v129, v24
	v_exp_f32_e32 v16, v16
	v_mul_f32_e32 v17, 0x3fb8aa3b, v17
	v_fma_f32 v18, v18, s78, -v242
	v_fma_f32 v24, v40, s78, -v242
	v_mul_f32_e32 v24, 0x3fb8aa3b, v24
	v_exp_f32_e32 v130, v24
	v_exp_f32_e32 v17, v17
	v_mul_f32_e32 v18, 0x3fb8aa3b, v18
	v_fma_f32 v19, v19, s78, -v242
	v_fma_f32 v24, v41, s78, -v242
	v_mul_f32_e32 v24, 0x3fb8aa3b, v24
	v_exp_f32_e32 v131, v24
	v_exp_f32_e32 v18, v18
	v_mul_f32_e32 v19, 0x3fb8aa3b, v19
	v_fma_f32 v24, v42, s78, -v242
	v_mul_f32_e32 v24, 0x3fb8aa3b, v24
	v_exp_f32_e32 v148, v24
	v_exp_f32_e32 v19, v19
	v_fma_f32 v24, v43, s78, -v242
	v_mul_f32_e32 v24, 0x3fb8aa3b, v24
	v_exp_f32_e32 v149, v24
	v_fma_f32 v32, v32, s78, -v242
	v_mul_f32_e32 v32, 0x3fb8aa3b, v32
	v_fma_f32 v24, v44, s78, -v242
	v_mul_f32_e32 v24, 0x3fb8aa3b, v24
	v_exp_f32_e32 v126, v24
	v_exp_f32_e32 v32, v32
	v_fma_f32 v33, v33, s78, -v242
	v_mul_f32_e32 v33, 0x3fb8aa3b, v33
	v_fma_f32 v24, v45, s78, -v242
	v_mul_f32_e32 v24, 0x3fb8aa3b, v24
	v_exp_f32_e32 v127, v24
	v_exp_f32_e32 v33, v33
	v_fma_f32 v34, v34, s78, -v242
	v_mul_f32_e32 v34, 0x3fb8aa3b, v34
	v_fma_f32 v24, v46, s78, -v242
	v_mul_f32_e32 v24, 0x3fb8aa3b, v24
	v_exp_f32_e32 v144, v24
	v_exp_f32_e32 v34, v34
	v_fma_f32 v35, v35, s78, -v242
	v_mul_f32_e32 v35, 0x3fb8aa3b, v35
	v_fma_f32 v24, v47, s78, -v242
	v_mul_f32_e32 v24, 0x3fb8aa3b, v24
	v_exp_f32_e32 v145, v24
	v_exp_f32_e32 v35, v35
	v_fma_f32 v24, v76, s78, -v242
	v_mul_f32_e32 v24, 0x3fb8aa3b, v24
	v_exp_f32_e32 v146, v24
	s_nop 0
	v_fma_f32 v24, v77, s78, -v242
	v_mul_f32_e32 v24, 0x3fb8aa3b, v24
	v_exp_f32_e32 v147, v24
	s_nop 0
	v_fma_f32 v24, v78, s78, -v242
	v_mul_f32_e32 v24, 0x3fb8aa3b, v24
	v_exp_f32_e32 v150, v24
	s_nop 0
	v_fma_f32 v24, v79, s78, -v242
	v_mul_f32_e32 v24, 0x3fb8aa3b, v24
	v_exp_f32_e32 v151, v24
	s_nop 0
	v_fma_f32 v24, v28, s78, -v242
	v_mul_f32_e32 v24, 0x3fb8aa3b, v24
	v_exp_f32_e32 v28, v24
	s_nop 0
	v_fma_f32 v24, v29, s78, -v242
	v_mul_f32_e32 v24, 0x3fb8aa3b, v24
	v_exp_f32_e32 v29, v24
	s_nop 0
	ds_read_b128 v[24:27], v182
	ds_read_b128 v[40:43], v182 offset:16
	s_waitcnt lgkmcnt(1)
; #define LAS __attribute__((address_space(3)))
; #define ATT_FENCE() asm volatile("" ::: "memory")
; DI void attn_worker(unsigned char* ws, LAS unsigned char* lds, LAS unsigned* qctr, int wave) {
;     ...
;         v4i ix[3][2]; v4u vv[3][8];
; #pragma unroll
;         for (int ch = 0; ch < 2; ++ch) {
;             ix[ch][0] = *(const LAS v4i*)(idl + 64 * kg + 8 * ch); ix[ch][1] = *(const LAS v4i*)(idl + 64 * kg + 8 * ch + 4);
; #pragma unroll
;             for (int j = 0; j < 8; ++j) vv[ch][j] = *(const v4u*)(vbase + (size_t)ix[ch][j >> 2][j & 3] * KVD);
;             ATT_FENCE(); }
;     ...
;         float sum = 0.f;
; #pragma unroll
;         for (int kt = 0; kt < 16; ++kt)
; #pragma unroll
;             for (int e = 0; e < 4; ++e) { const bool ok = (64 * kq + 4 * kt + e) < nvalid; const float p = ok ? __expf(s[kt][e] - mx) : 0.f; s[kt][e] = p; sum += p; }
;         sum += __shfl_xor(sum, 16); sum += __shfl_xor(sum, 32);
	v_lshl_add_u32 v44, v24, 10, v252
	v_lshl_add_u32 v46, v25, 10, v252
	global_load_dwordx4 v[88:91], v44, s[100:101]
	global_load_dwordx4 v[92:95], v46, s[100:101]
	v_lshl_add_u32 v24, v26, 10, v252
	v_lshl_add_u32 v44, v27, 10, v252
	global_load_dwordx4 v[96:99], v24, s[100:101]
	global_load_dwordx4 v[100:103], v44, s[100:101]
	s_waitcnt lgkmcnt(0)
	v_lshl_add_u32 v24, v40, 10, v252
	v_lshl_add_u32 v26, v41, 10, v252
	global_load_dwordx4 v[104:107], v24, s[100:101]
	global_load_dwordx4 v[108:111], v26, s[100:101]
	v_lshl_add_u32 v24, v42, 10, v252
	v_lshl_add_u32 v26, v43, 10, v252
	global_load_dwordx4 v[112:115], v24, s[100:101]
	global_load_dwordx4 v[116:119], v26, s[100:101]
	ds_read_b128 v[42:45], v182 offset:32
	ds_read_b128 v[120:123], v182 offset:48
	s_waitcnt lgkmcnt(1)
	s_waitcnt lgkmcnt(0)
	v_lshl_add_u32 v80, v120, 10, v252
	v_add_f32_e32 v120, 0, v124
	v_add_f32_e32 v120, v125, v120
	v_add_f32_e32 v120, v128, v120
	v_add_f32_e32 v120, v129, v120
	v_add_f32_e32 v120, v130, v120
	v_add_f32_e32 v120, v131, v120
	v_add_f32_e32 v120, v148, v120
	v_add_f32_e32 v120, v149, v120
	v_add_f32_e32 v120, v126, v120
	v_add_f32_e32 v120, v127, v120
	v_add_f32_e32 v120, v144, v120
	v_add_f32_e32 v120, v145, v120
	v_add_f32_e32 v120, v146, v120
	v_add_f32_e32 v120, v147, v120
	v_add_f32_e32 v120, v150, v120
	v_add_f32_e32 v120, v151, v120
	v_add_f32_e32 v120, v28, v120
	v_add_f32_e32 v120, v29, v120
	v_add_f32_e32 v120, v30, v120
	v_add_f32_e32 v120, v31, v120
	v_add_f32_e32 v120, v16, v120
	v_lshl_add_u32 v82, v121, 10, v252
	v_add_f32_e32 v121, v17, v120
	v_mov_b32_e32 v120, v18
	v_add_f32_e32 v18, v120, v121
	v_mov_b32_e32 v121, v19
	v_fma_f32 v19, v20, s78, -v242
	v_fma_f32 v20, v21, s78, -v242
	v_mul_f32_e32 v19, 0x3fb8aa3b, v19
	v_mul_f32_e32 v20, 0x3fb8aa3b, v20
	v_exp_f32_e32 v19, v19
	v_exp_f32_e32 v20, v20
	v_add_f32_e32 v21, v121, v18
	v_lshl_add_u32 v24, v42, 10, v252
	v_mov_b32_e32 v18, v19
	v_mov_b32_e32 v19, v20
	v_fma_f32 v20, v22, s78, -v242
	v_mul_f32_e32 v20, 0x3fb8aa3b, v20
	v_fma_f32 v22, v23, s78, -v242
	v_exp_f32_e32 v20, v20
	v_mul_f32_e32 v22, 0x3fb8aa3b, v22
	v_exp_f32_e32 v22, v22
	v_add_f32_e32 v21, v18, v21
	v_add_f32_e32 v21, v19, v21
	v_add_f32_e32 v23, v20, v21
	v_mov_b32_e32 v21, v22
	v_fma_f32 v22, v36, s78, -v242
	v_mul_f32_e32 v22, 0x3fb8aa3b, v22
	v_fma_f32 v36, v37, s78, -v242
	v_exp_f32_e32 v22, v22
	v_mul_f32_e32 v36, 0x3fb8aa3b, v36
	v_exp_f32_e32 v36, v36
	v_add_f32_e32 v23, v21, v23
	v_add_f32_e32 v37, v22, v23
	v_mov_b32_e32 v23, v36
	v_fma_f32 v36, v38, s78, -v242
	v_mul_f32_e32 v36, 0x3fb8aa3b, v36
	v_exp_f32_e32 v36, v36
	v_fma_f32 v38, v39, s78, -v242
	v_mul_f32_e32 v38, 0x3fb8aa3b, v38
	v_exp_f32_e32 v38, v38
	v_add_f32_e32 v37, v23, v37
	s_nop 0
	v_add_f32_e32 v39, v36, v37
	v_lshl_add_u32 v26, v43, 10, v252
	v_mov_b32_e32 v37, v38
	v_add_f32_e32 v38, v37, v39
	v_fma_f32 v39, v60, s78, -v242
	v_mul_f32_e32 v39, 0x3fb8aa3b, v39
	v_exp_f32_e32 v152, v39
	v_fma_f32 v60, v61, s78, -v242
	v_mul_f32_e32 v60, 0x3fb8aa3b, v60
	v_exp_f32_e32 v153, v60
	v_add_f32_e32 v38, v32, v38
	v_add_f32_e32 v38, v33, v38
	v_add_f32_e32 v38, v34, v38
	v_fma_f32 v39, v62, s78, -v242
	v_mul_f32_e32 v39, 0x3fb8aa3b, v39
	v_exp_f32_e32 v156, v39
	v_add_f32_e32 v38, v35, v38
	v_add_f32_e32 v38, v152, v38
	v_fma_f32 v60, v63, s78, -v242
	v_mul_f32_e32 v60, 0x3fb8aa3b, v60
	v_exp_f32_e32 v60, v60
	v_add_f32_e32 v38, v153, v38
	v_fma_f32 v39, v52, s78, -v242
	v_mul_f32_e32 v39, 0x3fb8aa3b, v39
	v_exp_f32_e32 v154, v39
	v_fma_f32 v52, v53, s78, -v242
	v_mul_f32_e32 v52, 0x3fb8aa3b, v52
	v_mov_b32_e32 v157, v60
	v_exp_f32_e32 v155, v52
	v_add_f32_e32 v38, v156, v38
	v_fma_f32 v39, v54, s78, -v242
	v_mul_f32_e32 v39, 0x3fb8aa3b, v39
	v_exp_f32_e32 v158, v39
	v_add_f32_e32 v38, v157, v38
	v_add_f32_e32 v38, v154, v38
	v_fma_f32 v52, v55, s78, -v242
	v_mul_f32_e32 v52, 0x3fb8aa3b, v52
	v_exp_f32_e32 v52, v52
	v_add_f32_e32 v38, v155, v38
	v_fma_f32 v39, v48, s78, -v242
	v_mul_f32_e32 v39, 0x3fb8aa3b, v39
	v_fma_f32 v48, v49, s78, -v242
	v_exp_f32_e32 v160, v39
	v_mul_f32_e32 v48, 0x3fb8aa3b, v48
	v_exp_f32_e32 v161, v48
	v_add_f32_e32 v38, v158, v38
	v_mov_b32_e32 v159, v52
	v_fma_f32 v48, v51, s78, -v242
	v_fma_f32 v39, v50, s78, -v242
	v_mul_f32_e32 v39, 0x3fb8aa3b, v39
	v_exp_f32_e32 v164, v39
	v_mul_f32_e32 v48, 0x3fb8aa3b, v48
	v_exp_f32_e32 v165, v48
	v_add_f32_e32 v38, v159, v38
	v_fma_f32 v39, v56, s78, -v242
	v_mul_f32_e32 v39, 0x3fb8aa3b, v39
	v_fma_f32 v48, v57, s78, -v242
	v_exp_f32_e32 v162, v39
	v_mul_f32_e32 v48, 0x3fb8aa3b, v48
	v_exp_f32_e32 v163, v48
	v_add_f32_e32 v38, v160, v38
	v_fma_f32 v39, v58, s78, -v242
	v_mul_f32_e32 v39, 0x3fb8aa3b, v39
	v_fma_f32 v48, v59, s78, -v242
	v_exp_f32_e32 v166, v39
	v_mul_f32_e32 v48, 0x3fb8aa3b, v48
	v_exp_f32_e32 v167, v48
	v_add_f32_e32 v38, v161, v38
	v_fma_f32 v39, v64, s78, -v242
	v_mul_f32_e32 v39, 0x3fb8aa3b, v39
	v_fma_f32 v48, v65, s78, -v242
	v_exp_f32_e32 v168, v39
	v_mul_f32_e32 v48, 0x3fb8aa3b, v48
	v_exp_f32_e32 v169, v48
	v_add_f32_e32 v38, v164, v38
	v_fma_f32 v39, v66, s78, -v242
	v_mul_f32_e32 v39, 0x3fb8aa3b, v39
	v_fma_f32 v48, v67, s78, -v242
	v_exp_f32_e32 v170, v39
	v_mul_f32_e32 v48, 0x3fb8aa3b, v48
	v_exp_f32_e32 v171, v48
	v_add_f32_e32 v38, v165, v38
	v_fma_f32 v39, v72, s78, -v242
	v_mul_f32_e32 v39, 0x3fb8aa3b, v39
	v_fma_f32 v48, v73, s78, -v242
	v_exp_f32_e32 v72, v39
	v_mul_f32_e32 v48, 0x3fb8aa3b, v48
	v_exp_f32_e32 v73, v48
	v_add_f32_e32 v38, v162, v38
	v_fma_f32 v39, v74, s78, -v242
	v_mul_f32_e32 v39, 0x3fb8aa3b, v39
	v_fma_f32 v48, v75, s78, -v242
	v_exp_f32_e32 v74, v39
	v_mul_f32_e32 v48, 0x3fb8aa3b, v48
	v_exp_f32_e32 v75, v48
	v_add_f32_e32 v38, v163, v38
	v_fma_f32 v39, v68, s78, -v242
	v_add_f32_e32 v38, v166, v38
	v_mul_f32_e32 v39, 0x3fb8aa3b, v39
	v_fma_f32 v48, v69, s78, -v242
	v_add_f32_e32 v38, v167, v38
	v_exp_f32_e32 v68, v39
	v_mul_f32_e32 v48, 0x3fb8aa3b, v48
	v_add_f32_e32 v38, v168, v38
	v_exp_f32_e32 v69, v48
	v_add_f32_e32 v38, v169, v38
	v_add_f32_e32 v38, v170, v38
	v_add_f32_e32 v38, v171, v38
	v_fma_f32 v39, v70, s78, -v242
	v_add_f32_e32 v38, v72, v38
	v_mul_f32_e32 v39, 0x3fb8aa3b, v39
	v_fma_f32 v48, v71, s78, -v242
	v_add_f32_e32 v38, v73, v38
	v_exp_f32_e32 v39, v39
	v_mul_f32_e32 v48, 0x3fb8aa3b, v48
	v_add_f32_e32 v38, v74, v38
	v_exp_f32_e32 v48, v48
	v_add_f32_e32 v38, v75, v38
	v_add_f32_e32 v38, v68, v38
	v_add_f32_e32 v38, v69, v38
	v_mov_b32_e32 v70, v39
	v_add_f32_e32 v38, v70, v38
	v_mov_b32_e32 v71, v48
	s_branch .Latt_join
